# relu(rs*a)^2 = rs^2*relu(a)^2: P5 epilogue drops 64 packed multiplies (fused mode only), fused P6 residual applies rs^2 = 1/(ss1/1024+eps) via fma; fused P6 K-loop peeled
# baseline (speedup 1.0000x reference)
; __device__ __forceinline__ size_t tm_block(int pm, int ct, int nct) { return ((size_t)pm * nct + ct) * 32768; }
; __device__ __forceinline__ u32x4 pack8(const f32x4& v0, const f32x4& v1) { u32x4 w; w.x = cvt_pk_bf16(v0[0], v0[1]); w.y = cvt_pk_bf16(v0[2], v0[3]); w.z = cvt_pk_bf16(v1[0], v1[1]); w.w = cvt_pk_bf16(v1[2], v1[3]); return w; }
;     __device__ __forceinline__ void post(const f32x4 (&acc)[2][2][4][2], const float (&st)[8], const Unit& u, int wr, int wc, int fr, int fq) const {
;         const PieceOut po(scr, O, tm_block(u.pm, u.pn * 4 + wc, 64), wr, wc, fr, fq);
; #pragma unroll
;         for (int ai = 0; ai < 2; ++ai)
; #pragma unroll
;             for (int m = 0; m < 4; ++m) { const float rs = __builtin_amdgcn_rsqf(st[ai * 4 + m] * (1.0f / 1024.0f) + eps);
; #pragma unroll
;                 for (int bj = 0; bj < 2; ++bj) { f32x4 v0 = acc[ai][bj][m][0] * rs, v1 = acc[ai][bj][m][1] * rs;
; #pragma unroll
;                     for (int k = 0; k < 4; ++k) { const float a = fmaxf(v0[k], 0.f), b = fmaxf(v1[k], 0.f); v0[k] = a * a; v1[k] = b * b; }
;                     po.put(bj, pack8(v0, v1)); }
;                 po.flush<true>(ai, m); }
.LBB0_589:
	s_cmpk_lg_i32 s33, 0x100
	s_cbranch_scc1 .Lp5_epi_rs
	s_cmp_eq_u32 s35, 8
	s_cbranch_scc1 .Lp5_epi_nors

; __device__ __forceinline__ u32x4 pack8(const f32x4& v0, const f32x4& v1) { u32x4 w; w.x = cvt_pk_bf16(v0[0], v0[1]); w.y = cvt_pk_bf16(v0[2], v0[3]); w.z = cvt_pk_bf16(v1[0], v1[1]); w.w = cvt_pk_bf16(v1[2], v1[3]); return w; }
;     __device__ __forceinline__ void post(const f32x4 (&acc)[2][2][4][2], const float (&st)[8], const Unit& u, int wr, int wc, int fr, int fq) const {
;     ...
;             for (int m = 0; m < 4; ++m) { const float rs = __builtin_amdgcn_rsqf(st[ai * 4 + m] * (1.0f / 1024.0f) + eps);
; #pragma unroll
;                 for (int bj = 0; bj < 2; ++bj) { f32x4 v0 = acc[ai][bj][m][0] * rs, v1 = acc[ai][bj][m][1] * rs;
; #pragma unroll
;                     for (int k = 0; k < 4; ++k) { const float a = fmaxf(v0[k], 0.f), b = fmaxf(v1[k], 0.f); v0[k] = a * a; v1[k] = b * b; }
;                     po.put(bj, pack8(v0, v1)); }
;                 po.flush<true>(ai, m); }
; template <class Epi, class Sched, bool ALIGN_EPI = false, bool SP2 = false>
; __device__ __forceinline__ void gemm_phase(PG8_LAS unsigned char* lds, const Gemm g, const Sched& S, const Epi& E) {
;     ...
;         if constexpr (!Epi::AFTER_DRAIN) { if constexpr (Epi::HAS_PRE) { E.post(acc, pre_st, cur, wr, wc, fr, fq); if (has_next) E.pre(pre_st, nxt, wr, wc, fr, fq); } else E(acc, cur, wr, wc, fr, fq); S.done(cur); }
.Lp5_epi_join:
	s_cbranch_vccnz .LBB0_578
	s_lshl_b32 s4, s18, 8
	s_ashr_i32 s5, s4, 31
	v_lshl_add_u64 v[2:3], s[4:5], 2, v[140:141]
	global_load_dword v164, v[2:3], off
	global_load_dword v163, v[2:3], off offset:64
	global_load_dword v162, v[2:3], off offset:128
	global_load_dword v161, v[2:3], off offset:192
	global_load_dword v160, v[2:3], off offset:512
	global_load_dword v159, v[2:3], off offset:576
	global_load_dword v152, v[2:3], off offset:640
	global_load_dword v150, v[2:3], off offset:704
	s_andn2_b64 vcc, exec, s[10:11]
	s_cbranch_vccnz .LBB0_577
	s_barrier
	s_branch .LBB0_577
.Lp5_epi_nors:
	s_waitcnt vmcnt(0)
	v_fmamk_f32 v164, v164, 0x3a800000, v156
	v_rsq_f32_e32 v164, v164
	s_lshl_b32 s17, s25, 2
	s_or_b32 s26, s17, s48
	s_ashr_i32 s25, s24, 31
	v_max_f32_e32 v122, 0, v122
	v_mul_f32_e32 v165, v122, v122
	v_max_f32_e32 v122, 0, v127
	v_max_f32_e32 v123, 0, v123
	v_max_f32_e32 v124, 0, v124
	v_max_f32_e32 v126, 0, v126
	v_mul_f32_e32 v122, v122, v122
	v_mul_f32_e32 v127, v123, v123
	v_max_f32_e32 v123, 0, v128
	v_mul_f32_e32 v128, v124, v124
	v_max_f32_e32 v124, 0, v129
	v_max_f32_e32 v125, 0, v125
	v_mul_f32_e32 v126, v126, v126
	v_mul_f32_e32 v123, v123, v123
	v_mul_f32_e32 v124, v124, v124
	v_mul_f32_e32 v125, v125, v125
	v_cvt_pk_bf16_f32 v122, v126, v122
	v_max_f32_e32 v114, 0, v114
	v_cvt_pk_bf16_f32 v123, v123, v124
	v_cvt_pk_bf16_f32 v124, v165, v127
	v_cvt_pk_bf16_f32 v125, v128, v125
	ds_write_b128 v157, v[122:125]
	v_mul_f32_e32 v122, v114, v114
	v_max_f32_e32 v114, 0, v119
	v_max_f32_e32 v115, 0, v115
	v_max_f32_e32 v116, 0, v116
	s_ashr_i32 s27, s26, 31
	v_max_f32_e32 v118, 0, v118
	v_mul_f32_e32 v114, v114, v114
	v_mul_f32_e32 v119, v115, v115
	v_max_f32_e32 v115, 0, v120
	v_mul_f32_e32 v120, v116, v116
	v_max_f32_e32 v116, 0, v121
	v_max_f32_e32 v117, 0, v117
	s_lshl_b64 s[24:25], s[24:25], 21
	s_lshl_b64 s[26:27], s[26:27], 15
	v_mul_f32_e32 v118, v118, v118
	v_mul_f32_e32 v115, v115, v115
	v_mul_f32_e32 v116, v116, v116
	v_mul_f32_e32 v117, v117, v117
	v_cvt_pk_bf16_f32 v114, v118, v114
	s_add_u32 s17, s38, s24
	v_cvt_pk_bf16_f32 v115, v115, v116
	v_cvt_pk_bf16_f32 v116, v122, v119
	v_cvt_pk_bf16_f32 v117, v120, v117
	ds_write_b128 v157, v[114:117] offset:64
	v_fmamk_f32 v114, v163, 0x3a800000, v156
	s_addc_u32 s19, s39, s25
	v_rsq_f32_e32 v124, v114
	s_add_u32 s17, s17, s26
	ds_read_b128 v[116:119], v158
	ds_read_b128 v[120:123], v158 offset:1152
	s_addc_u32 s19, s19, s27
	s_add_u32 s24, s17, s14
	s_addc_u32 s25, s19, s15
	v_lshl_add_u64 v[114:115], s[24:25], 0, v[138:139]
	v_max_f32_e32 v106, 0, v106
	s_waitcnt lgkmcnt(1)
	global_store_dwordx4 v[114:115], v[116:119], off nt
	s_waitcnt lgkmcnt(0)
	global_store_dwordx4 v[114:115], v[120:123], off offset:1024 nt
	v_mul_f32_e32 v116, v106, v106
	v_max_f32_e32 v106, 0, v111
	v_max_f32_e32 v107, 0, v107
	v_max_f32_e32 v108, 0, v108
	v_max_f32_e32 v110, 0, v110
	v_mul_f32_e32 v106, v106, v106
	v_mul_f32_e32 v111, v107, v107
	v_max_f32_e32 v107, 0, v112
	v_mul_f32_e32 v112, v108, v108
	v_max_f32_e32 v108, 0, v113
	v_max_f32_e32 v109, 0, v109
	v_mul_f32_e32 v110, v110, v110
	v_mul_f32_e32 v107, v107, v107
	v_mul_f32_e32 v108, v108, v108
	v_mul_f32_e32 v109, v109, v109
	v_cvt_pk_bf16_f32 v106, v110, v106
	v_max_f32_e32 v98, 0, v98
	v_max_f32_e32 v99, 0, v99
	v_max_f32_e32 v100, 0, v100
	v_cvt_pk_bf16_f32 v107, v107, v108
	v_cvt_pk_bf16_f32 v108, v116, v111
	v_cvt_pk_bf16_f32 v109, v112, v109
	ds_write_b128 v157, v[106:109]
	v_mul_f32_e32 v106, v98, v98
	v_max_f32_e32 v98, 0, v103
	v_mul_f32_e32 v103, v99, v99
	v_max_f32_e32 v99, 0, v104
	v_mul_f32_e32 v104, v100, v100
	v_max_f32_e32 v100, 0, v105
	v_max_f32_e32 v102, 0, v102
	v_mul_f32_e32 v98, v98, v98
	v_mul_f32_e32 v99, v99, v99
	v_max_f32_e32 v101, 0, v101
	v_mul_f32_e32 v100, v100, v100
	v_mul_f32_e32 v102, v102, v102
	v_mul_f32_e32 v101, v101, v101
	v_cvt_pk_bf16_f32 v98, v102, v98
	v_cvt_pk_bf16_f32 v99, v99, v100
	v_cvt_pk_bf16_f32 v100, v106, v103
	v_fmamk_f32 v106, v162, 0x3a800000, v156
	v_cvt_pk_bf16_f32 v101, v104, v101
	ds_write_b128 v157, v[98:101] offset:64
	v_rsq_f32_e32 v106, v106
	ds_read_b128 v[98:101], v158
	ds_read_b128 v[102:105], v158 offset:1152
	s_waitcnt lgkmcnt(1)
	global_store_dwordx4 v[114:115], v[98:101], off offset:2048 nt
	s_waitcnt lgkmcnt(0)
	global_store_dwordx4 v[114:115], v[102:105], off offset:3072 nt
	v_max_f32_e32 v90, 0, v90
	v_mul_f32_e32 v98, v90, v90
	v_max_f32_e32 v90, 0, v95
	v_max_f32_e32 v91, 0, v91
	v_max_f32_e32 v92, 0, v92
	v_max_f32_e32 v94, 0, v94
	v_mul_f32_e32 v90, v90, v90
	v_mul_f32_e32 v95, v91, v91
	v_max_f32_e32 v91, 0, v96
	v_mul_f32_e32 v96, v92, v92
	v_max_f32_e32 v92, 0, v97
	v_max_f32_e32 v93, 0, v93
	v_mul_f32_e32 v94, v94, v94
	v_mul_f32_e32 v91, v91, v91
	v_mul_f32_e32 v92, v92, v92
	v_mul_f32_e32 v93, v93, v93
	v_cvt_pk_bf16_f32 v90, v94, v90
	v_max_f32_e32 v82, 0, v82
	v_max_f32_e32 v83, 0, v83
	v_max_f32_e32 v84, 0, v84
	v_cvt_pk_bf16_f32 v91, v91, v92
	v_cvt_pk_bf16_f32 v92, v98, v95
	v_cvt_pk_bf16_f32 v93, v96, v93
	ds_write_b128 v157, v[90:93]
	v_mul_f32_e32 v90, v82, v82
	v_max_f32_e32 v82, 0, v87
	v_mul_f32_e32 v87, v83, v83
	v_max_f32_e32 v83, 0, v88
	v_mul_f32_e32 v88, v84, v84
	v_max_f32_e32 v84, 0, v89
	v_max_f32_e32 v86, 0, v86
	v_mul_f32_e32 v82, v82, v82
	v_mul_f32_e32 v83, v83, v83
	v_max_f32_e32 v85, 0, v85
	v_mul_f32_e32 v84, v84, v84
	v_mul_f32_e32 v86, v86, v86
	v_mul_f32_e32 v85, v85, v85
	v_cvt_pk_bf16_f32 v82, v86, v82
	v_cvt_pk_bf16_f32 v83, v83, v84
	v_cvt_pk_bf16_f32 v84, v90, v87
	v_fmamk_f32 v90, v161, 0x3a800000, v156
	v_cvt_pk_bf16_f32 v85, v88, v85
	ds_write_b128 v157, v[82:85] offset:64
	v_rsq_f32_e32 v90, v90
	ds_read_b128 v[82:85], v158
	ds_read_b128 v[86:89], v158 offset:1152
	v_add_co_u32_e32 v92, vcc, s53, v114
	s_nop 0
	s_nop 0
	v_addc_co_u32_e32 v93, vcc, 0, v115, vcc
	v_max_f32_e32 v74, 0, v74
	s_waitcnt lgkmcnt(1)
; __device__ __forceinline__ u32x4 pack8(const f32x4& v0, const f32x4& v1) { u32x4 w; w.x = cvt_pk_bf16(v0[0], v0[1]); w.y = cvt_pk_bf16(v0[2], v0[3]); w.z = cvt_pk_bf16(v1[0], v1[1]); w.w = cvt_pk_bf16(v1[2], v1[3]); return w; }
;     __device__ __forceinline__ void post(const f32x4 (&acc)[2][2][4][2], const float (&st)[8], const Unit& u, int wr, int wc, int fr, int fq) const {
;     ...
;             for (int m = 0; m < 4; ++m) { const float rs = __builtin_amdgcn_rsqf(st[ai * 4 + m] * (1.0f / 1024.0f) + eps);
; #pragma unroll
;                 for (int bj = 0; bj < 2; ++bj) { f32x4 v0 = acc[ai][bj][m][0] * rs, v1 = acc[ai][bj][m][1] * rs;
; #pragma unroll
;                     for (int k = 0; k < 4; ++k) { const float a = fmaxf(v0[k], 0.f), b = fmaxf(v1[k], 0.f); v0[k] = a * a; v1[k] = b * b; }
;                     po.put(bj, pack8(v0, v1)); }
;                 po.flush<true>(ai, m); }
	global_store_dwordx4 v[92:93], v[82:85], off nt
	s_waitcnt lgkmcnt(0)
	global_store_dwordx4 v[92:93], v[86:89], off offset:1024 nt
	v_mul_f32_e32 v82, v74, v74
	v_max_f32_e32 v74, 0, v79
	v_max_f32_e32 v75, 0, v75
	v_max_f32_e32 v76, 0, v76
	v_max_f32_e32 v78, 0, v78
	v_mul_f32_e32 v74, v74, v74
	v_mul_f32_e32 v79, v75, v75
	v_max_f32_e32 v75, 0, v80
	v_mul_f32_e32 v80, v76, v76
	v_max_f32_e32 v76, 0, v81
	v_max_f32_e32 v77, 0, v77
	v_mul_f32_e32 v78, v78, v78
	v_mul_f32_e32 v75, v75, v75
	v_mul_f32_e32 v76, v76, v76
	v_mul_f32_e32 v77, v77, v77
	v_cvt_pk_bf16_f32 v74, v78, v74
	v_max_f32_e32 v66, 0, v66
	v_max_f32_e32 v67, 0, v67
	v_max_f32_e32 v68, 0, v68
	v_cvt_pk_bf16_f32 v75, v75, v76
	v_cvt_pk_bf16_f32 v76, v82, v79
	v_cvt_pk_bf16_f32 v77, v80, v77
	ds_write_b128 v157, v[74:77]
	v_mul_f32_e32 v74, v66, v66
	v_max_f32_e32 v66, 0, v71
	v_mul_f32_e32 v71, v67, v67
	v_max_f32_e32 v67, 0, v72
	v_mul_f32_e32 v72, v68, v68
	v_max_f32_e32 v68, 0, v73
	v_max_f32_e32 v70, 0, v70
	v_mul_f32_e32 v66, v66, v66
	v_mul_f32_e32 v67, v67, v67
	v_max_f32_e32 v69, 0, v69
	v_mul_f32_e32 v68, v68, v68
	v_mul_f32_e32 v70, v70, v70
	v_mul_f32_e32 v69, v69, v69
	v_cvt_pk_bf16_f32 v66, v70, v66
	v_cvt_pk_bf16_f32 v67, v67, v68
	v_cvt_pk_bf16_f32 v68, v74, v71
	v_fmamk_f32 v74, v160, 0x3a800000, v156
	v_cvt_pk_bf16_f32 v69, v72, v69
	ds_write_b128 v157, v[66:69] offset:64
	v_rsq_f32_e32 v74, v74
	ds_read_b128 v[66:69], v158
	ds_read_b128 v[70:73], v158 offset:1152
	s_waitcnt lgkmcnt(1)
	global_store_dwordx4 v[92:93], v[66:69], off offset:2048 nt
	s_waitcnt lgkmcnt(0)
	global_store_dwordx4 v[92:93], v[70:73], off offset:3072 nt
	v_max_f32_e32 v58, 0, v58
	v_mul_f32_e32 v66, v58, v58
	v_max_f32_e32 v58, 0, v63
	v_max_f32_e32 v59, 0, v59
	v_max_f32_e32 v60, 0, v60
	v_max_f32_e32 v62, 0, v62
	v_mul_f32_e32 v58, v58, v58
	v_mul_f32_e32 v63, v59, v59
	v_max_f32_e32 v59, 0, v64
	v_mul_f32_e32 v64, v60, v60
	v_max_f32_e32 v60, 0, v65
	v_max_f32_e32 v61, 0, v61
	v_mul_f32_e32 v62, v62, v62
	v_mul_f32_e32 v59, v59, v59
	v_mul_f32_e32 v60, v60, v60
	v_mul_f32_e32 v61, v61, v61
	v_cvt_pk_bf16_f32 v58, v62, v58
	v_max_f32_e32 v50, 0, v50
	v_max_f32_e32 v51, 0, v51
	v_max_f32_e32 v52, 0, v52
	v_cvt_pk_bf16_f32 v59, v59, v60
	v_cvt_pk_bf16_f32 v60, v66, v63
	v_cvt_pk_bf16_f32 v61, v64, v61
	ds_write_b128 v157, v[58:61]
	v_mul_f32_e32 v58, v50, v50
	v_max_f32_e32 v50, 0, v55
	v_mul_f32_e32 v55, v51, v51
	v_max_f32_e32 v51, 0, v56
	v_mul_f32_e32 v56, v52, v52
	v_max_f32_e32 v52, 0, v57
	v_max_f32_e32 v53, 0, v53
	v_max_f32_e32 v54, 0, v54
	v_mul_f32_e32 v50, v50, v50
	v_mul_f32_e32 v51, v51, v51
	v_mul_f32_e32 v52, v52, v52
	v_mul_f32_e32 v53, v53, v53
	v_fmamk_f32 v60, v159, 0x3a800000, v156
	v_mul_f32_e32 v54, v54, v54
	v_cvt_pk_bf16_f32 v50, v54, v50
	v_cvt_pk_bf16_f32 v51, v51, v52
	v_cvt_pk_bf16_f32 v52, v58, v55
	v_cvt_pk_bf16_f32 v53, v56, v53
	ds_write_b128 v157, v[50:53] offset:64
	v_rsq_f32_e32 v60, v60
	ds_read_b128 v[50:53], v158
	ds_read_b128 v[54:57], v158 offset:1152
	v_add_co_u32_e32 v58, vcc, s47, v114
	s_nop 0
	s_nop 0
	v_addc_co_u32_e32 v59, vcc, 0, v115, vcc
	v_add_co_u32_e32 v62, vcc, s54, v114
	s_nop 0
	s_nop 0
	v_addc_co_u32_e32 v63, vcc, 0, v115, vcc
	v_max_f32_e32 v42, 0, v42
	s_waitcnt lgkmcnt(1)
	global_store_dwordx4 v[62:63], v[50:53], off offset:-4096 nt
	s_waitcnt lgkmcnt(0)
; __device__ __forceinline__ u32x4 pack8(const f32x4& v0, const f32x4& v1) { u32x4 w; w.x = cvt_pk_bf16(v0[0], v0[1]); w.y = cvt_pk_bf16(v0[2], v0[3]); w.z = cvt_pk_bf16(v1[0], v1[1]); w.w = cvt_pk_bf16(v1[2], v1[3]); return w; }
;     __device__ __forceinline__ void post(const f32x4 (&acc)[2][2][4][2], const float (&st)[8], const Unit& u, int wr, int wc, int fr, int fq) const {
;     ...
;             for (int m = 0; m < 4; ++m) { const float rs = __builtin_amdgcn_rsqf(st[ai * 4 + m] * (1.0f / 1024.0f) + eps);
; #pragma unroll
;                 for (int bj = 0; bj < 2; ++bj) { f32x4 v0 = acc[ai][bj][m][0] * rs, v1 = acc[ai][bj][m][1] * rs;
; #pragma unroll
;                     for (int k = 0; k < 4; ++k) { const float a = fmaxf(v0[k], 0.f), b = fmaxf(v1[k], 0.f); v0[k] = a * a; v1[k] = b * b; }
;                     po.put(bj, pack8(v0, v1)); }
;                 po.flush<true>(ai, m); }
	global_store_dwordx4 v[58:59], v[54:57], off offset:1024 nt
	v_mul_f32_e32 v50, v42, v42
	v_max_f32_e32 v42, 0, v47
	v_max_f32_e32 v43, 0, v43
	v_max_f32_e32 v44, 0, v44
	v_max_f32_e32 v46, 0, v46
	v_mul_f32_e32 v42, v42, v42
	v_mul_f32_e32 v47, v43, v43
	v_max_f32_e32 v43, 0, v48
	v_mul_f32_e32 v48, v44, v44
	v_max_f32_e32 v44, 0, v49
	v_max_f32_e32 v45, 0, v45
	v_mul_f32_e32 v46, v46, v46
	v_mul_f32_e32 v43, v43, v43
	v_mul_f32_e32 v44, v44, v44
	v_mul_f32_e32 v45, v45, v45
	v_cvt_pk_bf16_f32 v42, v46, v42
	v_max_f32_e32 v34, 0, v34
	v_max_f32_e32 v35, 0, v35
	v_max_f32_e32 v36, 0, v36
	v_cvt_pk_bf16_f32 v43, v43, v44
	v_cvt_pk_bf16_f32 v44, v50, v47
	v_cvt_pk_bf16_f32 v45, v48, v45
	ds_write_b128 v157, v[42:45]
	v_mul_f32_e32 v42, v34, v34
	v_max_f32_e32 v34, 0, v39
	v_mul_f32_e32 v39, v35, v35
	v_max_f32_e32 v35, 0, v40
	v_mul_f32_e32 v40, v36, v36
	v_max_f32_e32 v36, 0, v41
	v_max_f32_e32 v38, 0, v38
	v_mul_f32_e32 v34, v34, v34
	v_mul_f32_e32 v35, v35, v35
	v_max_f32_e32 v37, 0, v37
	v_mul_f32_e32 v36, v36, v36
	v_mul_f32_e32 v38, v38, v38
	v_mul_f32_e32 v37, v37, v37
	v_cvt_pk_bf16_f32 v34, v38, v34
	v_cvt_pk_bf16_f32 v35, v35, v36
	v_cvt_pk_bf16_f32 v36, v42, v39
	v_fmamk_f32 v42, v152, 0x3a800000, v156
	v_cvt_pk_bf16_f32 v37, v40, v37
	ds_write_b128 v157, v[34:37] offset:64
	v_rsq_f32_e32 v42, v42
	ds_read_b128 v[34:37], v158
	ds_read_b128 v[38:41], v158 offset:1152
	s_waitcnt lgkmcnt(1)
	global_store_dwordx4 v[58:59], v[34:37], off offset:2048 nt
	s_waitcnt lgkmcnt(0)
	global_store_dwordx4 v[58:59], v[38:41], off offset:3072 nt
	v_max_f32_e32 v26, 0, v26
	v_mul_f32_e32 v34, v26, v26
	v_max_f32_e32 v26, 0, v31
	v_max_f32_e32 v27, 0, v27
	v_max_f32_e32 v28, 0, v28
	v_max_f32_e32 v30, 0, v30
	v_mul_f32_e32 v26, v26, v26
	v_mul_f32_e32 v31, v27, v27
	v_max_f32_e32 v27, 0, v32
	v_mul_f32_e32 v32, v28, v28
	v_max_f32_e32 v28, 0, v33
	v_max_f32_e32 v29, 0, v29
	v_mul_f32_e32 v30, v30, v30
	v_mul_f32_e32 v27, v27, v27
	v_mul_f32_e32 v28, v28, v28
	v_mul_f32_e32 v29, v29, v29
	v_cvt_pk_bf16_f32 v26, v30, v26
	v_max_f32_e32 v18, 0, v18
	v_max_f32_e32 v19, 0, v19
	v_max_f32_e32 v20, 0, v20
	v_cvt_pk_bf16_f32 v27, v27, v28
	v_cvt_pk_bf16_f32 v28, v34, v31
	v_cvt_pk_bf16_f32 v29, v32, v29
	ds_write_b128 v157, v[26:29]
	v_mul_f32_e32 v26, v18, v18
	v_max_f32_e32 v18, 0, v23
	v_mul_f32_e32 v23, v19, v19
	v_max_f32_e32 v19, 0, v24
	v_mul_f32_e32 v24, v20, v20
	v_max_f32_e32 v20, 0, v25
	v_max_f32_e32 v22, 0, v22
	v_mul_f32_e32 v18, v18, v18
	v_mul_f32_e32 v19, v19, v19
	v_max_f32_e32 v21, 0, v21
	v_mul_f32_e32 v20, v20, v20
	v_mul_f32_e32 v22, v22, v22
	v_mul_f32_e32 v21, v21, v21
	v_cvt_pk_bf16_f32 v18, v22, v18
	v_cvt_pk_bf16_f32 v19, v19, v20
	v_cvt_pk_bf16_f32 v20, v26, v23
	v_fmamk_f32 v26, v150, 0x3a800000, v156
	v_cvt_pk_bf16_f32 v21, v24, v21
	ds_write_b128 v157, v[18:21] offset:64
	v_rsq_f32_e32 v26, v26
	ds_read_b128 v[18:21], v158
	ds_read_b128 v[22:25], v158 offset:1152
	s_waitcnt lgkmcnt(1)
	global_store_dwordx4 v[62:63], v[18:21], off nt
	s_waitcnt lgkmcnt(0)
	global_store_dwordx4 v[62:63], v[22:25], off offset:1024 nt
	v_max_f32_e32 v10, 0, v10
	v_mul_f32_e32 v18, v10, v10
	v_max_f32_e32 v10, 0, v15
	v_max_f32_e32 v11, 0, v11
	v_max_f32_e32 v12, 0, v12
	v_max_f32_e32 v14, 0, v14
	v_mul_f32_e32 v10, v10, v10
	v_mul_f32_e32 v15, v11, v11
	v_max_f32_e32 v11, 0, v16
	v_mul_f32_e32 v16, v12, v12
	v_max_f32_e32 v12, 0, v17
	v_max_f32_e32 v13, 0, v13
	v_mul_f32_e32 v14, v14, v14
	v_mul_f32_e32 v11, v11, v11
	v_mul_f32_e32 v12, v12, v12
	v_mul_f32_e32 v13, v13, v13
	v_cvt_pk_bf16_f32 v10, v14, v10
	v_max_f32_e32 v2, 0, v2
	v_max_f32_e32 v3, 0, v3
	v_max_f32_e32 v4, 0, v4
	v_cvt_pk_bf16_f32 v11, v11, v12
	v_cvt_pk_bf16_f32 v12, v18, v15
	v_cvt_pk_bf16_f32 v13, v16, v13
	ds_write_b128 v157, v[10:13]
	v_mul_f32_e32 v10, v2, v2
	v_max_f32_e32 v2, 0, v7
	v_mul_f32_e32 v7, v3, v3
	v_max_f32_e32 v3, 0, v8
	v_mul_f32_e32 v8, v4, v4
	v_max_f32_e32 v4, 0, v9
	v_max_f32_e32 v5, 0, v5
	v_max_f32_e32 v6, 0, v6
	v_mul_f32_e32 v2, v2, v2
	v_mul_f32_e32 v3, v3, v3
	v_mul_f32_e32 v4, v4, v4
	v_mul_f32_e32 v5, v5, v5
	v_mul_f32_e32 v6, v6, v6
	v_cvt_pk_bf16_f32 v2, v6, v2
	v_cvt_pk_bf16_f32 v3, v3, v4
	v_cvt_pk_bf16_f32 v4, v10, v7
	v_cvt_pk_bf16_f32 v5, v8, v5
	ds_write_b128 v157, v[2:5] offset:64
	ds_read_b128 v[2:5], v158
	ds_read_b128 v[6:9], v158 offset:1152
	s_andn2_b64 vcc, exec, s[4:5]
	s_mov_b64 s[4:5], -1
	s_waitcnt lgkmcnt(1)
	global_store_dwordx4 v[62:63], v[2:5], off offset:2048 nt
	s_waitcnt lgkmcnt(0)
	global_store_dwordx4 v[62:63], v[6:9], off offset:3072 nt
	s_branch .Lp5_epi_join

; #define PG8_STAGE(bufoff, gbase, voff) do { _Pragma("unroll") for (int _i = 0; _i < 2; ++_i) \
;         __builtin_amdgcn_global_load_lds((const unsigned*)((const char*)(gbase) + (voff)[_i]), (PG8_LAS unsigned*)(lds + (bufoff) + ldsw + _i * 8192), 16, 0, 0); } while (0)
; #define PG8_LDA(dst, b, h) do { _Pragma("unroll") for (int m = 0; m < 4; ++m) _Pragma("unroll") for (int k = 0; k < 2; ++k) dst[m][k] = *(const PG8_LAS bf16x8*)(lds + PG8_SA(b, h) + aoff + m * 2048 + k * 1024); } while (0)
; #define PG8_LDB(dst, b, h) do { _Pragma("unroll") for (int n = 0; n < 2; ++n) _Pragma("unroll") for (int k = 0; k < 2; ++k) dst[n][k] = *(const PG8_LAS bf16x8*)(lds + PG8_SB(b, h) + boff + n * 2048 + k * 1024); } while (0)
; #define PG8_MMA(ai, bj, At, Bt) do { __builtin_amdgcn_s_setprio(1); _Pragma("unroll") for (int m = 0; m < 4; ++m) _Pragma("unroll") for (int n = 0; n < 2; ++n) _Pragma("unroll") for (int k = 0; k < 2; ++k) \
;         acc[ai][bj][m][n] = __builtin_amdgcn_mfma_f32_16x16x32_bf16(Bt[n][k], At[m][k], acc[ai][bj][m][n], 0, 0, 0); __builtin_amdgcn_s_setprio(0); } while (0)
; #define PG8_WAIT_V(n) asm volatile("s_waitcnt vmcnt(" #n ")" ::: "memory")
; #define PG8_WAIT_L(n) asm volatile("s_waitcnt lgkmcnt(" #n ")" ::: "memory")
; #define PG8_BAR __builtin_amdgcn_s_barrier()
; #define PG8_SCHED __builtin_amdgcn_sched_barrier(0)
; template <class Epi, class Sched, bool ALIGN_EPI = false, bool SP2 = false>
; __device__ __forceinline__ void gemm_phase(PG8_LAS unsigned char* lds, const Gemm g, const Sched& S, const Epi& E) {
;     ...
;     f32x4 acc[2][2][4][2];
; #pragma unroll
;     for (int a = 0; a < 2; ++a)
; #pragma unroll
;         for (int b = 0; b < 2; ++b)
; #pragma unroll
;             for (int m = 0; m < 4; ++m)
; #pragma unroll
;                 for (int n = 0; n < 2; ++n) acc[a][b][m][n] = (f32x4){0.f, 0.f, 0.f, 0.f};
;     ...
;             PG8_LDB(B0, 0, 0); PG8_LDB(B1, 0, 1); PG8_SCHED; PG8_LDA(At, 0, 0); PG8_STAGE(PG8_SA(1, 1), a1 + hstep, voffA);
;             PG8_WAIT_V(8); PG8_WAIT_L(0); PG8_BAR; PG8_MMA(0, 0, At, B0); PG8_MMA(0, 1, At, B1); PG8_BAR; PG8_SCHED;
;             PG8_LDA(At, 0, 1); PG8_STAGE(PG8_SB(0, 0), b2, voffB); PG8_STAGE(PG8_SB(0, 1), b2 + hstepB, voffB); PG8_STAGE(PG8_SA(0, 0), a2, voffA);
;             PG8_WAIT_V(8); PG8_WAIT_L(0); PG8_BAR; PG8_MMA(1, 0, At, B0); PG8_MMA(1, 1, At, B1); PG8_BAR; PG8_SCHED;
.LBB0_725:
	s_ashr_i32 s29, s28, 31
	s_lshl_b64 s[42:43], s[28:29], 21
	s_add_u32 s42, s38, s42
	s_addc_u32 s43, s39, s43
	s_and_b64 s[44:45], s[6:7], exec
	s_cselect_b32 s27, s43, s51
	s_cselect_b32 s29, s42, s50
	s_ashr_i32 s37, s36, 31
	s_lshl_b64 s[44:45], s[36:37], 21
	s_add_u32 s44, s60, s44
	s_addc_u32 s45, s61, s45
	s_and_b64 s[52:53], s[6:7], exec
	s_cselect_b32 s37, s45, s65
	s_cselect_b32 s47, s44, s64
	s_add_u32 s50, s50, 0xc000
	s_addc_u32 s51, s51, 0
	s_add_u32 s49, s64, 0x10000
	s_addc_u32 s52, s65, 0
	s_mov_b32 s53, -2
	ds_read_b128 v[130:133], v209
	ds_read_b128 v[134:137], v209 offset:1024
	ds_read_b128 v[138:141], v209 offset:2048
	ds_read_b128 v[142:145], v209 offset:3072
	ds_read_b128 v[146:149], v210
	ds_read_b128 v[150:153], v210 offset:1024
	ds_read_b128 v[154:157], v210 offset:2048
	ds_read_b128 v[158:161], v210 offset:3072
	s_add_u32 s54, s50, 0x4000
	s_addc_u32 s55, s51, 0
	s_cmp_eq_u32 s53, 60
	s_cselect_b32 s68, s29, s54
	s_cselect_b32 s69, s27, s55
	s_cselect_b32 s66, s47, s49
	s_cselect_b32 s67, s37, s52
	s_add_u32 s64, s68, 0x8000
	s_addc_u32 s65, s69, 0
	s_add_i32 m0, s1, 0xc000
	ds_read_b128 v[162:165], v211
	ds_read_b128 v[166:169], v211 offset:1024
	ds_read_b128 v[170:173], v211 offset:2048
	ds_read_b128 v[174:177], v211 offset:3072
	ds_read_b128 v[178:181], v211 offset:4096
	ds_read_b128 v[182:185], v211 offset:5120
	ds_read_b128 v[224:227], v211 offset:6144
	ds_read_b128 v[228:231], v211 offset:7168
	global_load_lds_dwordx4 v198, s[50:51]
	s_add_i32 m0, s1, 0xe000
	s_nop 0
	global_load_lds_dwordx4 v200, s[50:51]
	s_waitcnt vmcnt(8)
	s_waitcnt lgkmcnt(0)
	s_setprio 1
	s_barrier
	v_mfma_f32_16x16x32_bf16 v[126:129], v[130:133], v[162:165], 0
	v_mfma_f32_16x16x32_bf16 v[122:125], v[138:141], v[162:165], 0
	v_mfma_f32_16x16x32_bf16 v[110:113], v[130:133], v[170:173], 0
	v_mfma_f32_16x16x32_bf16 v[106:109], v[138:141], v[170:173], 0
	v_mfma_f32_16x16x32_bf16 v[94:97], v[130:133], v[178:181], 0
	v_mfma_f32_16x16x32_bf16 v[90:93], v[138:141], v[178:181], 0
	v_mfma_f32_16x16x32_bf16 v[78:81], v[130:133], v[224:227], 0
	v_mfma_f32_16x16x32_bf16 v[74:77], v[138:141], v[224:227], 0
	v_mfma_f32_16x16x32_bf16 v[126:129], v[134:137], v[166:169], v[126:129]
	v_mfma_f32_16x16x32_bf16 v[122:125], v[142:145], v[166:169], v[122:125]
	v_mfma_f32_16x16x32_bf16 v[110:113], v[134:137], v[174:177], v[110:113]
	v_mfma_f32_16x16x32_bf16 v[106:109], v[142:145], v[174:177], v[106:109]
	v_mfma_f32_16x16x32_bf16 v[94:97], v[134:137], v[182:185], v[94:97]
	v_mfma_f32_16x16x32_bf16 v[90:93], v[142:145], v[182:185], v[90:93]
	v_mfma_f32_16x16x32_bf16 v[78:81], v[134:137], v[228:231], v[78:81]
	v_mfma_f32_16x16x32_bf16 v[74:77], v[142:145], v[228:231], v[74:77]
	s_setprio 0
	s_setprio 1
	v_mfma_f32_16x16x32_bf16 v[118:121], v[146:149], v[162:165], 0
	v_mfma_f32_16x16x32_bf16 v[114:117], v[154:157], v[162:165], 0
	v_mfma_f32_16x16x32_bf16 v[102:105], v[146:149], v[170:173], 0
	v_mfma_f32_16x16x32_bf16 v[98:101], v[154:157], v[170:173], 0
	v_mfma_f32_16x16x32_bf16 v[86:89], v[146:149], v[178:181], 0
	v_mfma_f32_16x16x32_bf16 v[82:85], v[154:157], v[178:181], 0
	v_mfma_f32_16x16x32_bf16 v[70:73], v[146:149], v[224:227], 0
	v_mfma_f32_16x16x32_bf16 v[66:69], v[154:157], v[224:227], 0
	v_mfma_f32_16x16x32_bf16 v[118:121], v[150:153], v[166:169], v[118:121]
	v_mfma_f32_16x16x32_bf16 v[114:117], v[158:161], v[166:169], v[114:117]
	v_mfma_f32_16x16x32_bf16 v[102:105], v[150:153], v[174:177], v[102:105]
	v_mfma_f32_16x16x32_bf16 v[98:101], v[158:161], v[174:177], v[98:101]
	v_mfma_f32_16x16x32_bf16 v[86:89], v[150:153], v[182:185], v[86:89]
	v_mfma_f32_16x16x32_bf16 v[82:85], v[158:161], v[182:185], v[82:85]
	v_mfma_f32_16x16x32_bf16 v[70:73], v[150:153], v[228:231], v[70:73]
	v_mfma_f32_16x16x32_bf16 v[66:69], v[158:161], v[228:231], v[66:69]
	s_barrier
	s_setprio 0
	s_add_i32 s54, s74, s0
	s_mov_b32 m0, s54
	ds_read_b128 v[162:165], v211 offset:16384
	ds_read_b128 v[166:169], v211 offset:17408
	ds_read_b128 v[170:173], v211 offset:18432
	ds_read_b128 v[174:177], v211 offset:19456
	ds_read_b128 v[178:181], v211 offset:20480
	ds_read_b128 v[182:185], v211 offset:21504
	ds_read_b128 v[224:227], v211 offset:22528
	ds_read_b128 v[228:231], v211 offset:23552
	global_load_lds_dwordx4 v188, s[66:67]
	s_add_i32 m0, s54, 0x2000
	s_add_u32 s54, s66, 0x1000
	s_addc_u32 s55, s67, 0
	s_add_i32 s89, s75, s0
	global_load_lds_dwordx4 v192, s[66:67]
	s_mov_b32 m0, s89
	s_nop 0
	global_load_lds_dwordx4 v188, s[54:55]
	s_add_i32 m0, s89, 0x2000
	s_nop 0
	global_load_lds_dwordx4 v192, s[54:55]
	s_mov_b32 m0, s1
	s_nop 0
	global_load_lds_dwordx4 v186, s[68:69]
	s_mov_b32 m0, s3
	s_nop 0
	global_load_lds_dwordx4 v190, s[68:69]
	s_waitcnt vmcnt(8)
	s_waitcnt lgkmcnt(0)
	s_setprio 1
	s_barrier
; #define PG8_STAGE(bufoff, gbase, voff) do { _Pragma("unroll") for (int _i = 0; _i < 2; ++_i) \
;         __builtin_amdgcn_global_load_lds((const unsigned*)((const char*)(gbase) + (voff)[_i]), (PG8_LAS unsigned*)(lds + (bufoff) + ldsw + _i * 8192), 16, 0, 0); } while (0)
; #define PG8_LDA(dst, b, h) do { _Pragma("unroll") for (int m = 0; m < 4; ++m) _Pragma("unroll") for (int k = 0; k < 2; ++k) dst[m][k] = *(const PG8_LAS bf16x8*)(lds + PG8_SA(b, h) + aoff + m * 2048 + k * 1024); } while (0)
; #define PG8_LDB(dst, b, h) do { _Pragma("unroll") for (int n = 0; n < 2; ++n) _Pragma("unroll") for (int k = 0; k < 2; ++k) dst[n][k] = *(const PG8_LAS bf16x8*)(lds + PG8_SB(b, h) + boff + n * 2048 + k * 1024); } while (0)
; #define PG8_MMA(ai, bj, At, Bt) do { __builtin_amdgcn_s_setprio(1); _Pragma("unroll") for (int m = 0; m < 4; ++m) _Pragma("unroll") for (int n = 0; n < 2; ++n) _Pragma("unroll") for (int k = 0; k < 2; ++k) \
;         acc[ai][bj][m][n] = __builtin_amdgcn_mfma_f32_16x16x32_bf16(Bt[n][k], At[m][k], acc[ai][bj][m][n], 0, 0, 0); __builtin_amdgcn_s_setprio(0); } while (0)
; #define PG8_WAIT_V(n) asm volatile("s_waitcnt vmcnt(" #n ")" ::: "memory")
; #define PG8_WAIT_L(n) asm volatile("s_waitcnt lgkmcnt(" #n ")" ::: "memory")
; #define PG8_BAR __builtin_amdgcn_s_barrier()
; #define PG8_SCHED __builtin_amdgcn_sched_barrier(0)
; template <class Epi, class Sched, bool ALIGN_EPI = false, bool SP2 = false>
; __device__ __forceinline__ void gemm_phase(PG8_LAS unsigned char* lds, const Gemm g, const Sched& S, const Epi& E) {
;     ...
;             PG8_LDA(At, 0, 1); PG8_STAGE(PG8_SB(0, 0), b2, voffB); PG8_STAGE(PG8_SB(0, 1), b2 + hstepB, voffB); PG8_STAGE(PG8_SA(0, 0), a2, voffA);
;             PG8_WAIT_V(8); PG8_WAIT_L(0); PG8_BAR; PG8_MMA(1, 0, At, B0); PG8_MMA(1, 1, At, B1); PG8_BAR; PG8_SCHED;
;             PG8_LDB(B0, 1, 0); PG8_LDB(B1, 1, 1); PG8_SCHED; PG8_LDA(At, 1, 0); PG8_STAGE(PG8_SA(0, 1), a2 + hstep, voffA);
;             PG8_WAIT_V(8); PG8_WAIT_L(0); PG8_BAR; PG8_MMA(0, 0, At, B0); PG8_MMA(0, 1, At, B1); PG8_BAR; PG8_SCHED;
	v_mfma_f32_16x16x32_bf16 v[62:65], v[130:133], v[162:165], 0
	v_mfma_f32_16x16x32_bf16 v[58:61], v[138:141], v[162:165], 0
	v_mfma_f32_16x16x32_bf16 v[46:49], v[130:133], v[170:173], 0
	v_mfma_f32_16x16x32_bf16 v[42:45], v[138:141], v[170:173], 0
	v_mfma_f32_16x16x32_bf16 v[30:33], v[130:133], v[178:181], 0
	v_mfma_f32_16x16x32_bf16 v[26:29], v[138:141], v[178:181], 0
	v_mfma_f32_16x16x32_bf16 v[14:17], v[130:133], v[224:227], 0
	v_mfma_f32_16x16x32_bf16 v[10:13], v[138:141], v[224:227], 0
	v_mfma_f32_16x16x32_bf16 v[62:65], v[134:137], v[166:169], v[62:65]
	v_mfma_f32_16x16x32_bf16 v[58:61], v[142:145], v[166:169], v[58:61]
	v_mfma_f32_16x16x32_bf16 v[46:49], v[134:137], v[174:177], v[46:49]
	v_mfma_f32_16x16x32_bf16 v[42:45], v[142:145], v[174:177], v[42:45]
	v_mfma_f32_16x16x32_bf16 v[30:33], v[134:137], v[182:185], v[30:33]
	v_mfma_f32_16x16x32_bf16 v[26:29], v[142:145], v[182:185], v[26:29]
	v_mfma_f32_16x16x32_bf16 v[14:17], v[134:137], v[228:231], v[14:17]
	v_mfma_f32_16x16x32_bf16 v[10:13], v[142:145], v[228:231], v[10:13]
	s_setprio 0
	s_setprio 1
	v_mfma_f32_16x16x32_bf16 v[54:57], v[146:149], v[162:165], 0
	v_mfma_f32_16x16x32_bf16 v[50:53], v[154:157], v[162:165], 0
	v_mfma_f32_16x16x32_bf16 v[38:41], v[146:149], v[170:173], 0
	v_mfma_f32_16x16x32_bf16 v[34:37], v[154:157], v[170:173], 0
	v_mfma_f32_16x16x32_bf16 v[22:25], v[146:149], v[178:181], 0
	v_mfma_f32_16x16x32_bf16 v[18:21], v[154:157], v[178:181], 0
	v_mfma_f32_16x16x32_bf16 v[6:9], v[146:149], v[224:227], 0
	v_mfma_f32_16x16x32_bf16 v[2:5], v[154:157], v[224:227], 0
	v_mfma_f32_16x16x32_bf16 v[54:57], v[150:153], v[166:169], v[54:57]
	v_mfma_f32_16x16x32_bf16 v[50:53], v[158:161], v[166:169], v[50:53]
	v_mfma_f32_16x16x32_bf16 v[38:41], v[150:153], v[174:177], v[38:41]
	v_mfma_f32_16x16x32_bf16 v[34:37], v[158:161], v[174:177], v[34:37]
	v_mfma_f32_16x16x32_bf16 v[22:25], v[150:153], v[182:185], v[22:25]
	v_mfma_f32_16x16x32_bf16 v[18:21], v[158:161], v[182:185], v[18:21]
	v_mfma_f32_16x16x32_bf16 v[6:9], v[150:153], v[228:231], v[6:9]
	v_mfma_f32_16x16x32_bf16 v[2:5], v[158:161], v[228:231], v[2:5]
	s_barrier
	s_setprio 0
	s_add_i32 s89, 0, 0x18000
	s_add_i32 s90, 0, 0x1c000
	v_add_u32_e32 v142, s89, v214
	v_add_u32_e32 v158, s90, v214
	ds_read_b128 v[130:133], v142
	ds_read_b128 v[134:137], v142 offset:1024
	ds_read_b128 v[138:141], v142 offset:2048
	ds_read_b128 v[142:145], v142 offset:3072
	ds_read_b128 v[146:149], v158
	ds_read_b128 v[150:153], v158 offset:1024
	ds_read_b128 v[154:157], v158 offset:2048
	ds_read_b128 v[158:161], v158 offset:3072
	s_add_u32 s54, s68, 0x4000
	s_addc_u32 s55, s69, 0
	s_mov_b32 m0, s56
	ds_read_b128 v[162:165], v211 offset:32768
	ds_read_b128 v[166:169], v211 offset:33792
	ds_read_b128 v[170:173], v211 offset:34816
	ds_read_b128 v[174:177], v211 offset:35840
	ds_read_b128 v[178:181], v211 offset:36864
	ds_read_b128 v[182:185], v211 offset:37888
	ds_read_b128 v[224:227], v211 offset:38912
	ds_read_b128 v[228:231], v211 offset:39936
	global_load_lds_dwordx4 v186, s[54:55]
	s_mov_b32 m0, s57
	s_nop 0
	global_load_lds_dwordx4 v190, s[54:55]
	s_waitcnt vmcnt(8)
	s_waitcnt lgkmcnt(0)
	s_setprio 1
	s_barrier
	v_mfma_f32_16x16x32_bf16 v[126:129], v[130:133], v[162:165], v[126:129]
	v_mfma_f32_16x16x32_bf16 v[122:125], v[138:141], v[162:165], v[122:125]
	v_mfma_f32_16x16x32_bf16 v[110:113], v[130:133], v[170:173], v[110:113]
	v_mfma_f32_16x16x32_bf16 v[106:109], v[138:141], v[170:173], v[106:109]
	v_mfma_f32_16x16x32_bf16 v[94:97], v[130:133], v[178:181], v[94:97]
	v_mfma_f32_16x16x32_bf16 v[90:93], v[138:141], v[178:181], v[90:93]
	v_mfma_f32_16x16x32_bf16 v[78:81], v[130:133], v[224:227], v[78:81]
	v_mfma_f32_16x16x32_bf16 v[74:77], v[138:141], v[224:227], v[74:77]
	v_mfma_f32_16x16x32_bf16 v[126:129], v[134:137], v[166:169], v[126:129]
	v_mfma_f32_16x16x32_bf16 v[122:125], v[142:145], v[166:169], v[122:125]
	v_mfma_f32_16x16x32_bf16 v[110:113], v[134:137], v[174:177], v[110:113]
	v_mfma_f32_16x16x32_bf16 v[106:109], v[142:145], v[174:177], v[106:109]
	v_mfma_f32_16x16x32_bf16 v[94:97], v[134:137], v[182:185], v[94:97]
	v_mfma_f32_16x16x32_bf16 v[90:93], v[142:145], v[182:185], v[90:93]
	v_mfma_f32_16x16x32_bf16 v[78:81], v[134:137], v[228:231], v[78:81]
	v_mfma_f32_16x16x32_bf16 v[74:77], v[142:145], v[228:231], v[74:77]
	s_setprio 0
	s_setprio 1
	v_mfma_f32_16x16x32_bf16 v[118:121], v[146:149], v[162:165], v[118:121]
	v_mfma_f32_16x16x32_bf16 v[114:117], v[154:157], v[162:165], v[114:117]
	v_mfma_f32_16x16x32_bf16 v[102:105], v[146:149], v[170:173], v[102:105]
	v_mfma_f32_16x16x32_bf16 v[98:101], v[154:157], v[170:173], v[98:101]
	v_mfma_f32_16x16x32_bf16 v[86:89], v[146:149], v[178:181], v[86:89]
	v_mfma_f32_16x16x32_bf16 v[82:85], v[154:157], v[178:181], v[82:85]
	v_mfma_f32_16x16x32_bf16 v[70:73], v[146:149], v[224:227], v[70:73]
	v_mfma_f32_16x16x32_bf16 v[66:69], v[154:157], v[224:227], v[66:69]
	v_mfma_f32_16x16x32_bf16 v[118:121], v[150:153], v[166:169], v[118:121]
	v_mfma_f32_16x16x32_bf16 v[114:117], v[158:161], v[166:169], v[114:117]
	v_mfma_f32_16x16x32_bf16 v[102:105], v[150:153], v[174:177], v[102:105]
	v_mfma_f32_16x16x32_bf16 v[98:101], v[158:161], v[174:177], v[98:101]
	v_mfma_f32_16x16x32_bf16 v[86:89], v[150:153], v[182:185], v[86:89]
	v_mfma_f32_16x16x32_bf16 v[82:85], v[158:161], v[182:185], v[82:85]
	v_mfma_f32_16x16x32_bf16 v[70:73], v[150:153], v[228:231], v[70:73]
	v_mfma_f32_16x16x32_bf16 v[66:69], v[158:161], v[228:231], v[66:69]
	s_barrier
; #define PG8_STAGE(bufoff, gbase, voff) do { _Pragma("unroll") for (int _i = 0; _i < 2; ++_i) \
;         __builtin_amdgcn_global_load_lds((const unsigned*)((const char*)(gbase) + (voff)[_i]), (PG8_LAS unsigned*)(lds + (bufoff) + ldsw + _i * 8192), 16, 0, 0); } while (0)
; #define PG8_LDA(dst, b, h) do { _Pragma("unroll") for (int m = 0; m < 4; ++m) _Pragma("unroll") for (int k = 0; k < 2; ++k) dst[m][k] = *(const PG8_LAS bf16x8*)(lds + PG8_SA(b, h) + aoff + m * 2048 + k * 1024); } while (0)
; #define PG8_MMA(ai, bj, At, Bt) do { __builtin_amdgcn_s_setprio(1); _Pragma("unroll") for (int m = 0; m < 4; ++m) _Pragma("unroll") for (int n = 0; n < 2; ++n) _Pragma("unroll") for (int k = 0; k < 2; ++k) \
;         acc[ai][bj][m][n] = __builtin_amdgcn_mfma_f32_16x16x32_bf16(Bt[n][k], At[m][k], acc[ai][bj][m][n], 0, 0, 0); __builtin_amdgcn_s_setprio(0); } while (0)
; #define PG8_WAIT_V(n) asm volatile("s_waitcnt vmcnt(" #n ")" ::: "memory")
; #define PG8_WAIT_L(n) asm volatile("s_waitcnt lgkmcnt(" #n ")" ::: "memory")
; #define PG8_BAR __builtin_amdgcn_s_barrier()
; #define PG8_SCHED __builtin_amdgcn_sched_barrier(0)
; template <class Epi, class Sched, bool ALIGN_EPI = false, bool SP2 = false>
; __device__ __forceinline__ void gemm_phase(PG8_LAS unsigned char* lds, const Gemm g, const Sched& S, const Epi& E) {
;     ...
;             PG8_LDA(At, 1, 1); PG8_STAGE(PG8_SB(1, 0), b3, voffB); PG8_STAGE(PG8_SB(1, 1), b3 + hstepB, voffB); PG8_STAGE(PG8_SA(1, 0), a3, voffA);
;             PG8_WAIT_V(8); PG8_WAIT_L(0); PG8_BAR; PG8_MMA(1, 0, At, B0); PG8_MMA(1, 1, At, B1); PG8_BAR; PG8_SCHED;
	s_setprio 0
	s_add_u32 s54, s66, 0x8000
	s_addc_u32 s55, s67, 0
	s_add_i32 s68, s89, s0
	s_mov_b32 m0, s68
	ds_read_b128 v[162:165], v211 offset:49152
	ds_read_b128 v[166:169], v211 offset:50176
	ds_read_b128 v[170:173], v211 offset:51200
	ds_read_b128 v[174:177], v211 offset:52224
	ds_read_b128 v[178:181], v211 offset:53248
	ds_read_b128 v[182:185], v211 offset:54272
	ds_read_b128 v[224:227], v211 offset:55296
	ds_read_b128 v[228:231], v211 offset:56320
	global_load_lds_dwordx4 v188, s[54:55]
	s_add_i32 m0, s68, 0x2000
	v_lshl_add_u64 v[206:207], s[54:55], 0, v[192:193]
	s_add_u32 s54, s66, 0x9000
	s_addc_u32 s55, s67, 0
	s_add_i32 s66, s90, s0
	global_load_lds_dwordx4 v[206:207], off
	s_mov_b32 m0, s66
	s_nop 0
	global_load_lds_dwordx4 v188, s[54:55]
	s_add_i32 m0, s66, 0x2000
	s_nop 0
	global_load_lds_dwordx4 v192, s[54:55]
	s_mov_b32 m0, s71
	s_nop 0
	global_load_lds_dwordx4 v186, s[64:65]
	s_mov_b32 m0, s72
	s_nop 0
	global_load_lds_dwordx4 v190, s[64:65]
	s_waitcnt vmcnt(8)
	s_waitcnt lgkmcnt(0)
	s_setprio 1
	s_barrier
	v_mfma_f32_16x16x32_bf16 v[62:65], v[130:133], v[162:165], v[62:65]
	v_mfma_f32_16x16x32_bf16 v[58:61], v[138:141], v[162:165], v[58:61]
	v_mfma_f32_16x16x32_bf16 v[46:49], v[130:133], v[170:173], v[46:49]
	v_mfma_f32_16x16x32_bf16 v[42:45], v[138:141], v[170:173], v[42:45]
	v_mfma_f32_16x16x32_bf16 v[30:33], v[130:133], v[178:181], v[30:33]
	v_mfma_f32_16x16x32_bf16 v[26:29], v[138:141], v[178:181], v[26:29]
	v_mfma_f32_16x16x32_bf16 v[14:17], v[130:133], v[224:227], v[14:17]
	v_mfma_f32_16x16x32_bf16 v[10:13], v[138:141], v[224:227], v[10:13]
	v_mfma_f32_16x16x32_bf16 v[62:65], v[134:137], v[166:169], v[62:65]
	v_mfma_f32_16x16x32_bf16 v[58:61], v[142:145], v[166:169], v[58:61]
	v_mfma_f32_16x16x32_bf16 v[46:49], v[134:137], v[174:177], v[46:49]
	v_mfma_f32_16x16x32_bf16 v[42:45], v[142:145], v[174:177], v[42:45]
	v_mfma_f32_16x16x32_bf16 v[30:33], v[134:137], v[182:185], v[30:33]
	v_mfma_f32_16x16x32_bf16 v[26:29], v[142:145], v[182:185], v[26:29]
	v_mfma_f32_16x16x32_bf16 v[14:17], v[134:137], v[228:231], v[14:17]
	v_mfma_f32_16x16x32_bf16 v[10:13], v[142:145], v[228:231], v[10:13]
	s_setprio 0
	s_setprio 1
	v_mfma_f32_16x16x32_bf16 v[54:57], v[146:149], v[162:165], v[54:57]
	v_mfma_f32_16x16x32_bf16 v[50:53], v[154:157], v[162:165], v[50:53]
	v_mfma_f32_16x16x32_bf16 v[38:41], v[146:149], v[170:173], v[38:41]
	v_mfma_f32_16x16x32_bf16 v[34:37], v[154:157], v[170:173], v[34:37]
	v_mfma_f32_16x16x32_bf16 v[22:25], v[146:149], v[178:181], v[22:25]
	v_mfma_f32_16x16x32_bf16 v[18:21], v[154:157], v[178:181], v[18:21]
	v_mfma_f32_16x16x32_bf16 v[6:9], v[146:149], v[224:227], v[6:9]
	v_mfma_f32_16x16x32_bf16 v[2:5], v[154:157], v[224:227], v[2:5]
	v_mfma_f32_16x16x32_bf16 v[54:57], v[150:153], v[166:169], v[54:57]
	v_mfma_f32_16x16x32_bf16 v[50:53], v[158:161], v[166:169], v[50:53]
	v_mfma_f32_16x16x32_bf16 v[38:41], v[150:153], v[174:177], v[38:41]
	v_mfma_f32_16x16x32_bf16 v[34:37], v[158:161], v[174:177], v[34:37]
	v_mfma_f32_16x16x32_bf16 v[22:25], v[150:153], v[182:185], v[22:25]
	v_mfma_f32_16x16x32_bf16 v[18:21], v[158:161], v[182:185], v[18:21]
	v_mfma_f32_16x16x32_bf16 v[6:9], v[150:153], v[228:231], v[6:9]
	v_mfma_f32_16x16x32_bf16 v[2:5], v[158:161], v[228:231], v[2:5]
	s_barrier
	s_setprio 0
	s_add_i32 s53, s53, 2
	s_add_u32 s50, s50, 0x10000
	s_addc_u32 s51, s51, 0
	s_add_u32 s49, s49, 0x10000
	s_addc_u32 s52, s52, 0

; #define UNPK0(q_) ((f32x4){bf_lo((q_).x), bf_hi((q_).x), bf_lo((q_).y), bf_hi((q_).y)})
; #define UNPK1(q_) ((f32x4){bf_lo((q_).z), bf_hi((q_).z), bf_lo((q_).w), bf_hi((q_).w)})
;     __device__ __forceinline__ void operator()(f32x4 (&acc)[2][2][4][2], const Unit& u, int wr, int wc, int fr, int fq) const {
;     ...
;         for (int ai = 0; ai < 2; ++ai)
; #pragma unroll
;             for (int m = 0; m < 4; ++m) { const int row = row0 + ai * HALF + m * 16; float sq = 0.f;
;                 pi.stage(rx[ai][m][0], rx[ai][m][1]); const u32x4 x0 = pi.get(0), x1 = pi.get(1);
;                 asm volatile("" ::: "memory");
; #pragma unroll
;                 for (int bj = 0; bj < 2; ++bj) { const u32x4 z4 = bj ? x1 : x0;
;                     const f32x4 o0 = UNPK0(z4) + acc[ai][bj][m][0], o1 = UNPK1(z4) + acc[ai][bj][m][1];
;                     acc[ai][bj][m][0] = o0; acc[ai][bj][m][1] = o1;
;                     sq += ((o0[0] * o0[0] + o0[1] * o0[1]) + (o0[2] * o0[2] + o0[3] * o0[3])) + ((o1[0] * o1[0] + o1[1] * o1[1]) + (o1[2] * o1[2] + o1[3] * o1[3])); }
;                 sq += __shfl_xor(sq, 16); sq += __shfl_xor(sq, 32);
;                 if (fq == 0) atomicAdd(ss + row, sq); }
.LBB0_729:
	s_lshl_b32 s29, s46, 2
	s_or_b32 s50, s29, s58
	s_lshl_b32 s27, s48, 8
	s_ashr_i32 s49, s48, 31
	s_ashr_i32 s51, s50, 31
	s_add_i32 s27, s27, s18
	s_lshl_b32 s40, s27, 2
	s_add_u32 s40, s12, s40
	s_addc_u32 s41, s13, 0
	s_sub_u32 s40, s40, 0x40000
	s_subb_u32 s41, s41, 0
	s_lshl_b64 s[52:53], s[48:49], 19
	s_lshl_b64 s[50:51], s[50:51], 15
	s_add_u32 s29, s62, s52
	s_addc_u32 s37, s63, s53
	s_add_u32 s29, s29, s50
	s_addc_u32 s37, s37, s51
	s_add_u32 s50, s29, s22
	s_addc_u32 s51, s37, s23
	v_lshl_add_u64 v[130:131], s[50:51], 0, v[196:197]
	global_load_dwordx4 v[224:227], v[130:131], off
	global_load_dwordx4 v[228:231], v[130:131], off offset:1024
	v_add_co_u32_e32 v132, vcc, s76, v130
	s_movk_i32 s29, 0x4000
	s_nop 0
	v_addc_co_u32_e32 v133, vcc, 0, v131, vcc
	v_add_co_u32_e32 v134, vcc, s29, v130
	global_load_dwordx4 v[178:181], v[130:131], off offset:2048
	global_load_dwordx4 v[182:185], v[130:131], off offset:3072
	v_addc_co_u32_e32 v135, vcc, 0, v131, vcc
	v_add_co_u32_e32 v136, vcc, s77, v130
	v_add_u32_e32 v223, v216, v213
	s_nop 0
	v_addc_co_u32_e32 v137, vcc, 0, v131, vcc
	global_load_dwordx4 v[170:173], v[132:133], off
	global_load_dwordx4 v[174:177], v[132:133], off offset:1024
	global_load_dwordx4 v[162:165], v[132:133], off offset:2048
	global_load_dwordx4 v[166:169], v[132:133], off offset:3072
	global_load_dwordx4 v[154:157], v[134:135], off offset:1024
	global_load_dwordx4 v[146:149], v[134:135], off offset:2048
	global_load_dwordx4 v[158:161], v[136:137], off offset:-4096
	global_load_dwordx4 v[150:153], v[134:135], off offset:3072
	global_load_dwordx4 v[138:141], v[136:137], off
	global_load_dwordx4 v[142:145], v[136:137], off offset:1024
	global_load_dwordx4 v[130:133], v[136:137], off offset:2048
	s_nop 0
	global_load_dwordx4 v[134:137], v[136:137], off offset:3072
	v_and_b32_e32 v207, 64, v217
	v_xor_b32_e32 v206, 16, v217
	v_add_u32_e32 v240, 64, v207
	v_cmp_lt_i32_e32 vcc, v206, v240
	v_lshlrev_b32_e32 v241, 2, v208
	global_load_dword v241, v241, s[40:41] offset:0
	v_lshlrev_b32_e32 v242, 2, v208
	global_load_dword v242, v242, s[40:41] offset:64
	v_lshlrev_b32_e32 v243, 2, v208
	global_load_dword v243, v243, s[40:41] offset:128
	v_lshlrev_b32_e32 v244, 2, v208
	global_load_dword v244, v244, s[40:41] offset:192
	v_lshlrev_b32_e32 v245, 2, v208
	global_load_dword v245, v245, s[40:41] offset:512
	v_lshlrev_b32_e32 v247, 2, v208
	global_load_dword v247, v247, s[40:41] offset:576
	s_waitcnt vmcnt(0)
	v_fmamk_f32 v241, v241, 0x3a800000, v219
	v_rcp_f32_e32 v241, v241
	v_fmamk_f32 v242, v242, 0x3a800000, v219
	v_rcp_f32_e32 v242, v242
	v_fmamk_f32 v243, v243, 0x3a800000, v219
	v_rcp_f32_e32 v243, v243
	v_fmamk_f32 v244, v244, 0x3a800000, v219
	v_rcp_f32_e32 v244, v244
	v_fmamk_f32 v245, v245, 0x3a800000, v219
	v_rcp_f32_e32 v245, v245
	v_fmamk_f32 v247, v247, 0x3a800000, v219
	v_rcp_f32_e32 v247, v247
	ds_write_b128 v222, v[224:227]
	ds_write_b128 v222, v[228:231] offset:1152
	ds_read_b128 v[226:229], v223
	ds_read_b128 v[230:233], v223 offset:64
	v_cndmask_b32_e32 v206, v217, v206, vcc
	v_lshlrev_b32_e32 v224, 2, v206
	s_waitcnt lgkmcnt(1)
	v_lshlrev_b32_e32 v206, 16, v226
	v_and_b32_e32 v207, 0xffff0000, v226
	v_lshlrev_b32_e32 v226, 16, v227
	v_and_b32_e32 v227, 0xffff0000, v227
	v_lshlrev_b32_e32 v234, 16, v228
	v_and_b32_e32 v235, 0xffff0000, v228
	v_lshlrev_b32_e32 v228, 16, v229
	v_and_b32_e32 v229, 0xffff0000, v229
	s_waitcnt lgkmcnt(0)
	v_lshlrev_b32_e32 v236, 16, v230
	v_and_b32_e32 v237, 0xffff0000, v230
	v_lshlrev_b32_e32 v230, 16, v231
	v_and_b32_e32 v231, 0xffff0000, v231
	v_lshlrev_b32_e32 v238, 16, v232
	v_and_b32_e32 v239, 0xffff0000, v232
	v_lshlrev_b32_e32 v232, 16, v233
	v_and_b32_e32 v233, 0xffff0000, v233
	v_fma_f32 v128, v128, v241, v226
	v_fma_f32 v129, v129, v241, v227
	v_fma_f32 v126, v126, v241, v206
	v_fma_f32 v127, v127, v241, v207
	v_fma_f32 v124, v124, v241, v228
	v_fma_f32 v125, v125, v241, v229
	v_fma_f32 v122, v122, v241, v234
	v_fma_f32 v123, v123, v241, v235
	v_fma_f32 v120, v120, v241, v230
	v_fma_f32 v121, v121, v241, v231
	v_fma_f32 v118, v118, v241, v236
	v_fma_f32 v119, v119, v241, v237
	v_fma_f32 v116, v116, v241, v232
	v_fma_f32 v117, v117, v241, v233
	v_fma_f32 v114, v114, v241, v238
	v_fma_f32 v115, v115, v241, v239
	v_mul_f32_e32 v206, v127, v127
	v_mul_f32_e32 v207, v129, v129
	v_mul_f32_e32 v225, v123, v123
	v_mul_f32_e32 v226, v125, v125
	v_mul_f32_e32 v227, v119, v119
	v_mul_f32_e32 v228, v121, v121
	v_mul_f32_e32 v229, v115, v115
	v_mul_f32_e32 v230, v117, v117
	v_fmac_f32_e32 v206, v126, v126
	v_fmac_f32_e32 v207, v128, v128
	v_fmac_f32_e32 v225, v122, v122
	v_fmac_f32_e32 v226, v124, v124
	v_fmac_f32_e32 v227, v118, v118
	v_fmac_f32_e32 v228, v120, v120
	v_fmac_f32_e32 v229, v114, v114
	v_fmac_f32_e32 v230, v116, v116
	v_add_f32_e32 v206, v206, v207
	v_add_f32_e32 v207, v225, v226
	v_add_f32_e32 v225, v227, v228
	v_add_f32_e32 v226, v229, v230
	v_add_f32_e32 v206, v206, v207
	v_add_f32_e32 v207, v225, v226
	v_add_f32_e32 v207, v206, v207
	ds_bpermute_b32 v225, v224, v207
	v_xor_b32_e32 v226, 32, v217
	v_cmp_lt_i32_e32 vcc, v226, v240
	v_or_b32_e32 v206, s27, v208
	s_nop 0
	v_cndmask_b32_e32 v227, v217, v226, vcc
	s_waitcnt lgkmcnt(0)
	v_add_f32_e32 v226, v207, v225
	v_lshlrev_b32_e32 v225, 2, v227
	ds_bpermute_b32 v227, v225, v226
	v_ashrrev_i32_e32 v207, 31, v206
	s_and_saveexec_b64 s[50:51], s[8:9]
	s_cbranch_execz .LBB0_731
	v_lshl_add_u64 v[228:229], v[206:207], 2, s[12:13]
	s_waitcnt lgkmcnt(0)
	v_add_f32_e32 v226, v226, v227
	global_atomic_add_f32 v[228:229], v226, off
; #define UNPK0(q_) ((f32x4){bf_lo((q_).x), bf_hi((q_).x), bf_lo((q_).y), bf_hi((q_).y)})
; #define UNPK1(q_) ((f32x4){bf_lo((q_).z), bf_hi((q_).z), bf_lo((q_).w), bf_hi((q_).w)})
;     __device__ __forceinline__ void operator()(f32x4 (&acc)[2][2][4][2], const Unit& u, int wr, int wc, int fr, int fq) const {
;     ...
;         for (int ai = 0; ai < 2; ++ai)
; #pragma unroll
;             for (int m = 0; m < 4; ++m) { const int row = row0 + ai * HALF + m * 16; float sq = 0.f;
;                 pi.stage(rx[ai][m][0], rx[ai][m][1]); const u32x4 x0 = pi.get(0), x1 = pi.get(1);
;                 asm volatile("" ::: "memory");
; #pragma unroll
;                 for (int bj = 0; bj < 2; ++bj) { const u32x4 z4 = bj ? x1 : x0;
;                     const f32x4 o0 = UNPK0(z4) + acc[ai][bj][m][0], o1 = UNPK1(z4) + acc[ai][bj][m][1];
;                     acc[ai][bj][m][0] = o0; acc[ai][bj][m][1] = o1;
;                     sq += ((o0[0] * o0[0] + o0[1] * o0[1]) + (o0[2] * o0[2] + o0[3] * o0[3])) + ((o1[0] * o1[0] + o1[1] * o1[1]) + (o1[2] * o1[2] + o1[3] * o1[3])); }
;                 sq += __shfl_xor(sq, 16); sq += __shfl_xor(sq, 32);
;                 if (fq == 0) atomicAdd(ss + row, sq); }
.LBB0_731:
	s_or_b64 exec, exec, s[50:51]
	ds_write_b128 v222, v[178:181]
	ds_write_b128 v222, v[182:185] offset:1152
	ds_read_b128 v[178:181], v223
	ds_read_b128 v[182:185], v223 offset:64
	s_waitcnt lgkmcnt(1)
	v_lshlrev_b32_e32 v226, 16, v178
	v_and_b32_e32 v227, 0xffff0000, v178
	v_lshlrev_b32_e32 v178, 16, v179
	v_and_b32_e32 v179, 0xffff0000, v179
	v_fma_f32 v112, v112, v242, v178
	v_fma_f32 v113, v113, v242, v179
	v_fma_f32 v110, v110, v242, v226
	v_fma_f32 v111, v111, v242, v227
	v_lshlrev_b32_e32 v178, 16, v180
	v_and_b32_e32 v179, 0xffff0000, v180
	v_lshlrev_b32_e32 v180, 16, v181
	v_and_b32_e32 v181, 0xffff0000, v181
	v_fma_f32 v106, v106, v242, v178
	v_fma_f32 v107, v107, v242, v179
	v_mul_f32_e32 v178, v111, v111
	v_mul_f32_e32 v179, v113, v113
	v_fma_f32 v108, v108, v242, v180
	v_fma_f32 v109, v109, v242, v181
	v_fmac_f32_e32 v178, v110, v110
	v_fmac_f32_e32 v179, v112, v112
	v_add_f32_e32 v178, v178, v179
	v_mul_f32_e32 v179, v107, v107
	v_mul_f32_e32 v180, v109, v109
	v_fmac_f32_e32 v179, v106, v106
	v_fmac_f32_e32 v180, v108, v108
	v_add_f32_e32 v179, v179, v180
	v_add_f32_e32 v226, v178, v179
	s_waitcnt lgkmcnt(0)
	v_lshlrev_b32_e32 v178, 16, v182
	v_and_b32_e32 v179, 0xffff0000, v182
	v_lshlrev_b32_e32 v180, 16, v183
	v_and_b32_e32 v181, 0xffff0000, v183
	v_fma_f32 v104, v104, v242, v180
	v_fma_f32 v105, v105, v242, v181
	v_fma_f32 v102, v102, v242, v178
	v_fma_f32 v103, v103, v242, v179
	v_lshlrev_b32_e32 v178, 16, v184
	v_and_b32_e32 v179, 0xffff0000, v184
	v_lshlrev_b32_e32 v180, 16, v185
	v_and_b32_e32 v181, 0xffff0000, v185
	v_fma_f32 v98, v98, v242, v178
	v_fma_f32 v99, v99, v242, v179
	v_mul_f32_e32 v178, v103, v103
	v_mul_f32_e32 v179, v105, v105
	v_fma_f32 v100, v100, v242, v180
	v_fma_f32 v101, v101, v242, v181
	v_fmac_f32_e32 v178, v102, v102
	v_fmac_f32_e32 v179, v104, v104
	v_add_f32_e32 v178, v178, v179
	v_mul_f32_e32 v179, v99, v99
	v_mul_f32_e32 v180, v101, v101
	v_fmac_f32_e32 v179, v98, v98
	v_fmac_f32_e32 v180, v100, v100
	v_add_f32_e32 v179, v179, v180
	v_add_f32_e32 v178, v178, v179
	v_add_f32_e32 v178, v226, v178
	ds_bpermute_b32 v179, v224, v178
	s_waitcnt lgkmcnt(0)
	v_add_f32_e32 v178, v178, v179
	ds_bpermute_b32 v179, v225, v178
	s_and_saveexec_b64 s[50:51], s[8:9]
	s_cbranch_execz .LBB0_733
	v_lshl_add_u64 v[180:181], v[206:207], 2, s[12:13]
	s_waitcnt lgkmcnt(0)
	v_add_f32_e32 v178, v178, v179
	global_atomic_add_f32 v[180:181], v178, off offset:64
.LBB0_733:
	s_or_b64 exec, exec, s[50:51]
	ds_write_b128 v222, v[170:173]
	ds_write_b128 v222, v[174:177] offset:1152
	ds_read_b128 v[170:173], v223
	ds_read_b128 v[174:177], v223 offset:64
	s_waitcnt lgkmcnt(1)
	v_lshlrev_b32_e32 v178, 16, v170
	v_and_b32_e32 v179, 0xffff0000, v170
	v_lshlrev_b32_e32 v170, 16, v171
	v_and_b32_e32 v171, 0xffff0000, v171
	v_lshlrev_b32_e32 v241, 2, v208
	global_load_dword v241, v241, s[40:41] offset:640
	v_lshlrev_b32_e32 v242, 2, v208
	global_load_dword v242, v242, s[40:41] offset:704
	v_fma_f32 v96, v96, v243, v170
	v_fma_f32 v97, v97, v243, v171
	v_fma_f32 v94, v94, v243, v178
	v_fma_f32 v95, v95, v243, v179
	v_lshlrev_b32_e32 v170, 16, v172
	v_and_b32_e32 v171, 0xffff0000, v172
	v_lshlrev_b32_e32 v172, 16, v173
	v_and_b32_e32 v173, 0xffff0000, v173
	v_fma_f32 v90, v90, v243, v170
	v_fma_f32 v91, v91, v243, v171
	v_mul_f32_e32 v170, v95, v95
	v_mul_f32_e32 v171, v97, v97
	v_fma_f32 v92, v92, v243, v172
	v_fma_f32 v93, v93, v243, v173
	v_fmac_f32_e32 v170, v94, v94
	v_fmac_f32_e32 v171, v96, v96
	v_add_f32_e32 v170, v170, v171
	v_mul_f32_e32 v171, v91, v91
	v_mul_f32_e32 v172, v93, v93
	v_fmac_f32_e32 v171, v90, v90
	v_fmac_f32_e32 v172, v92, v92
	v_add_f32_e32 v171, v171, v172
	v_add_f32_e32 v178, v170, v171
	s_waitcnt lgkmcnt(0)
	v_lshlrev_b32_e32 v170, 16, v174
	v_and_b32_e32 v171, 0xffff0000, v174
	v_lshlrev_b32_e32 v172, 16, v175
	v_and_b32_e32 v173, 0xffff0000, v175
	v_fma_f32 v88, v88, v243, v172
	v_fma_f32 v89, v89, v243, v173
	v_fma_f32 v86, v86, v243, v170
	v_fma_f32 v87, v87, v243, v171
	v_lshlrev_b32_e32 v170, 16, v176
	v_and_b32_e32 v171, 0xffff0000, v176
	v_lshlrev_b32_e32 v172, 16, v177
	v_and_b32_e32 v173, 0xffff0000, v177
	v_fma_f32 v82, v82, v243, v170
	v_fma_f32 v83, v83, v243, v171
	v_mul_f32_e32 v170, v87, v87
	v_mul_f32_e32 v171, v89, v89
	v_fma_f32 v84, v84, v243, v172
	v_fma_f32 v85, v85, v243, v173
	v_fmac_f32_e32 v170, v86, v86
	v_fmac_f32_e32 v171, v88, v88
	v_add_f32_e32 v170, v170, v171
	v_mul_f32_e32 v171, v83, v83
	v_mul_f32_e32 v172, v85, v85
	v_fmac_f32_e32 v171, v82, v82
	v_fmac_f32_e32 v172, v84, v84
	v_add_f32_e32 v171, v171, v172
	v_add_f32_e32 v170, v170, v171
	v_add_f32_e32 v170, v178, v170
	ds_bpermute_b32 v171, v224, v170
	s_waitcnt lgkmcnt(0)
	v_add_f32_e32 v170, v170, v171
	ds_bpermute_b32 v171, v225, v170
	s_and_saveexec_b64 s[50:51], s[8:9]
	s_cbranch_execz .LBB0_735
	v_lshl_add_u64 v[172:173], v[206:207], 2, s[12:13]
	s_waitcnt lgkmcnt(0)
	v_add_f32_e32 v170, v170, v171
	global_atomic_add_f32 v[172:173], v170, off offset:128
; #define UNPK0(q_) ((f32x4){bf_lo((q_).x), bf_hi((q_).x), bf_lo((q_).y), bf_hi((q_).y)})
; #define UNPK1(q_) ((f32x4){bf_lo((q_).z), bf_hi((q_).z), bf_lo((q_).w), bf_hi((q_).w)})
;     __device__ __forceinline__ void operator()(f32x4 (&acc)[2][2][4][2], const Unit& u, int wr, int wc, int fr, int fq) const {
;     ...
;         for (int ai = 0; ai < 2; ++ai)
; #pragma unroll
;             for (int m = 0; m < 4; ++m) { const int row = row0 + ai * HALF + m * 16; float sq = 0.f;
;                 pi.stage(rx[ai][m][0], rx[ai][m][1]); const u32x4 x0 = pi.get(0), x1 = pi.get(1);
;                 asm volatile("" ::: "memory");
; #pragma unroll
;                 for (int bj = 0; bj < 2; ++bj) { const u32x4 z4 = bj ? x1 : x0;
;                     const f32x4 o0 = UNPK0(z4) + acc[ai][bj][m][0], o1 = UNPK1(z4) + acc[ai][bj][m][1];
;                     acc[ai][bj][m][0] = o0; acc[ai][bj][m][1] = o1;
;                     sq += ((o0[0] * o0[0] + o0[1] * o0[1]) + (o0[2] * o0[2] + o0[3] * o0[3])) + ((o1[0] * o1[0] + o1[1] * o1[1]) + (o1[2] * o1[2] + o1[3] * o1[3])); }
;                 sq += __shfl_xor(sq, 16); sq += __shfl_xor(sq, 32);
;                 if (fq == 0) atomicAdd(ss + row, sq); }
.LBB0_735:
	s_or_b64 exec, exec, s[50:51]
	ds_write_b128 v222, v[162:165]
	ds_write_b128 v222, v[166:169] offset:1152
	ds_read_b128 v[162:165], v223
	ds_read_b128 v[166:169], v223 offset:64
	s_waitcnt lgkmcnt(1)
	v_lshlrev_b32_e32 v170, 16, v162
	v_and_b32_e32 v171, 0xffff0000, v162
	v_lshlrev_b32_e32 v162, 16, v163
	v_and_b32_e32 v163, 0xffff0000, v163
	v_fma_f32 v80, v80, v244, v162
	v_fma_f32 v81, v81, v244, v163
	v_fma_f32 v78, v78, v244, v170
	v_fma_f32 v79, v79, v244, v171
	v_lshlrev_b32_e32 v162, 16, v164
	v_and_b32_e32 v163, 0xffff0000, v164
	v_lshlrev_b32_e32 v164, 16, v165
	v_and_b32_e32 v165, 0xffff0000, v165
	v_fma_f32 v74, v74, v244, v162
	v_fma_f32 v75, v75, v244, v163
	v_mul_f32_e32 v162, v79, v79
	v_mul_f32_e32 v163, v81, v81
	v_fma_f32 v76, v76, v244, v164
	v_fma_f32 v77, v77, v244, v165
	v_fmac_f32_e32 v162, v78, v78
	v_fmac_f32_e32 v163, v80, v80
	v_add_f32_e32 v162, v162, v163
	v_mul_f32_e32 v163, v75, v75
	v_mul_f32_e32 v164, v77, v77
	v_fmac_f32_e32 v163, v74, v74
	v_fmac_f32_e32 v164, v76, v76
	v_add_f32_e32 v163, v163, v164
	v_add_f32_e32 v170, v162, v163
	s_waitcnt lgkmcnt(0)
	v_lshlrev_b32_e32 v162, 16, v166
	v_and_b32_e32 v163, 0xffff0000, v166
	v_lshlrev_b32_e32 v164, 16, v167
	v_and_b32_e32 v165, 0xffff0000, v167
	v_fma_f32 v72, v72, v244, v164
	v_fma_f32 v73, v73, v244, v165
	v_fma_f32 v70, v70, v244, v162
	v_fma_f32 v71, v71, v244, v163
	v_lshlrev_b32_e32 v162, 16, v168
	v_and_b32_e32 v163, 0xffff0000, v168
	v_lshlrev_b32_e32 v164, 16, v169
	v_and_b32_e32 v165, 0xffff0000, v169
	v_fma_f32 v66, v66, v244, v162
	v_fma_f32 v67, v67, v244, v163
	v_mul_f32_e32 v162, v71, v71
	v_mul_f32_e32 v163, v73, v73
	v_fma_f32 v68, v68, v244, v164
	v_fma_f32 v69, v69, v244, v165
	v_fmac_f32_e32 v162, v70, v70
	v_fmac_f32_e32 v163, v72, v72
	v_add_f32_e32 v162, v162, v163
	v_mul_f32_e32 v163, v67, v67
	v_mul_f32_e32 v164, v69, v69
	v_fmac_f32_e32 v163, v66, v66
	v_fmac_f32_e32 v164, v68, v68
	v_add_f32_e32 v163, v163, v164
	v_add_f32_e32 v162, v162, v163
	v_add_f32_e32 v162, v170, v162
	ds_bpermute_b32 v163, v224, v162
	s_waitcnt lgkmcnt(0)
	v_add_f32_e32 v162, v162, v163
	ds_bpermute_b32 v163, v225, v162
	s_and_saveexec_b64 s[50:51], s[8:9]
	s_cbranch_execz .LBB0_737
	v_lshl_add_u64 v[164:165], v[206:207], 2, s[12:13]
	s_waitcnt lgkmcnt(0)
	v_add_f32_e32 v162, v162, v163
	global_atomic_add_f32 v[164:165], v162, off offset:192
.LBB0_737:
	s_or_b64 exec, exec, s[50:51]
	ds_write_b128 v222, v[158:161]
	ds_write_b128 v222, v[154:157] offset:1152
	ds_read_b128 v[154:157], v223
	ds_read_b128 v[158:161], v223 offset:64
	s_waitcnt lgkmcnt(1)
	v_lshlrev_b32_e32 v162, 16, v154
	v_and_b32_e32 v163, 0xffff0000, v154
	v_lshlrev_b32_e32 v154, 16, v155
	v_and_b32_e32 v155, 0xffff0000, v155
	v_fma_f32 v64, v64, v245, v154
	v_fma_f32 v65, v65, v245, v155
	v_fma_f32 v62, v62, v245, v162
	v_fma_f32 v63, v63, v245, v163
	v_lshlrev_b32_e32 v154, 16, v156
	v_and_b32_e32 v155, 0xffff0000, v156
	v_lshlrev_b32_e32 v156, 16, v157
	v_and_b32_e32 v157, 0xffff0000, v157
	v_fma_f32 v58, v58, v245, v154
	v_fma_f32 v59, v59, v245, v155
	v_mul_f32_e32 v154, v63, v63
	v_mul_f32_e32 v155, v65, v65
	v_fma_f32 v60, v60, v245, v156
	v_fma_f32 v61, v61, v245, v157
	v_fmac_f32_e32 v154, v62, v62
	v_fmac_f32_e32 v155, v64, v64
	v_add_f32_e32 v154, v154, v155
	v_mul_f32_e32 v155, v59, v59
	v_mul_f32_e32 v156, v61, v61
	v_fmac_f32_e32 v155, v58, v58
	v_fmac_f32_e32 v156, v60, v60
	v_add_f32_e32 v155, v155, v156
	v_add_f32_e32 v162, v154, v155
	s_waitcnt lgkmcnt(0)
	v_lshlrev_b32_e32 v154, 16, v158
	v_and_b32_e32 v155, 0xffff0000, v158
	v_lshlrev_b32_e32 v156, 16, v159
	v_and_b32_e32 v157, 0xffff0000, v159
	v_fma_f32 v56, v56, v245, v156
	v_fma_f32 v57, v57, v245, v157
	v_fma_f32 v54, v54, v245, v154
	v_fma_f32 v55, v55, v245, v155
	v_lshlrev_b32_e32 v154, 16, v160
	v_and_b32_e32 v155, 0xffff0000, v160
	v_lshlrev_b32_e32 v156, 16, v161
	v_and_b32_e32 v157, 0xffff0000, v161
	v_fma_f32 v50, v50, v245, v154
	v_fma_f32 v51, v51, v245, v155
	v_mul_f32_e32 v154, v55, v55
	v_mul_f32_e32 v155, v57, v57
	v_fma_f32 v52, v52, v245, v156
	v_fma_f32 v53, v53, v245, v157
	v_fmac_f32_e32 v154, v54, v54
	v_fmac_f32_e32 v155, v56, v56
	v_add_f32_e32 v154, v154, v155
	v_mul_f32_e32 v155, v51, v51
	v_mul_f32_e32 v156, v53, v53
	v_fmac_f32_e32 v155, v50, v50
	v_fmac_f32_e32 v156, v52, v52
	v_add_f32_e32 v155, v155, v156
	v_add_f32_e32 v154, v154, v155
	v_add_f32_e32 v154, v162, v154
	ds_bpermute_b32 v155, v224, v154
	s_waitcnt lgkmcnt(0)
	v_add_f32_e32 v154, v154, v155
	ds_bpermute_b32 v155, v225, v154
	s_and_saveexec_b64 s[50:51], s[8:9]
	s_cbranch_execz .LBB0_739
	v_lshl_add_u64 v[156:157], v[206:207], 2, s[12:13]
	s_waitcnt lgkmcnt(0)
	v_add_f32_e32 v154, v154, v155
	global_atomic_add_f32 v[156:157], v154, off offset:512
; #define UNPK0(q_) ((f32x4){bf_lo((q_).x), bf_hi((q_).x), bf_lo((q_).y), bf_hi((q_).y)})
; #define UNPK1(q_) ((f32x4){bf_lo((q_).z), bf_hi((q_).z), bf_lo((q_).w), bf_hi((q_).w)})
;     __device__ __forceinline__ void operator()(f32x4 (&acc)[2][2][4][2], const Unit& u, int wr, int wc, int fr, int fq) const {
;     ...
;         for (int ai = 0; ai < 2; ++ai)
; #pragma unroll
;             for (int m = 0; m < 4; ++m) { const int row = row0 + ai * HALF + m * 16; float sq = 0.f;
;                 pi.stage(rx[ai][m][0], rx[ai][m][1]); const u32x4 x0 = pi.get(0), x1 = pi.get(1);
;                 asm volatile("" ::: "memory");
; #pragma unroll
;                 for (int bj = 0; bj < 2; ++bj) { const u32x4 z4 = bj ? x1 : x0;
;                     const f32x4 o0 = UNPK0(z4) + acc[ai][bj][m][0], o1 = UNPK1(z4) + acc[ai][bj][m][1];
;                     acc[ai][bj][m][0] = o0; acc[ai][bj][m][1] = o1;
;                     sq += ((o0[0] * o0[0] + o0[1] * o0[1]) + (o0[2] * o0[2] + o0[3] * o0[3])) + ((o1[0] * o1[0] + o1[1] * o1[1]) + (o1[2] * o1[2] + o1[3] * o1[3])); }
;                 sq += __shfl_xor(sq, 16); sq += __shfl_xor(sq, 32);
;                 if (fq == 0) atomicAdd(ss + row, sq); }
.LBB0_739:
	s_or_b64 exec, exec, s[50:51]
	ds_write_b128 v222, v[146:149]
	ds_write_b128 v222, v[150:153] offset:1152
	ds_read_b128 v[146:149], v223
	ds_read_b128 v[150:153], v223 offset:64
	s_waitcnt lgkmcnt(1)
	v_lshlrev_b32_e32 v154, 16, v146
	v_and_b32_e32 v155, 0xffff0000, v146
	v_lshlrev_b32_e32 v146, 16, v147
	v_and_b32_e32 v147, 0xffff0000, v147
	v_fma_f32 v48, v48, v247, v146
	v_fma_f32 v49, v49, v247, v147
	v_fma_f32 v46, v46, v247, v154
	v_fma_f32 v47, v47, v247, v155
	v_lshlrev_b32_e32 v146, 16, v148
	v_and_b32_e32 v147, 0xffff0000, v148
	v_lshlrev_b32_e32 v148, 16, v149
	v_and_b32_e32 v149, 0xffff0000, v149
	v_fma_f32 v42, v42, v247, v146
	v_fma_f32 v43, v43, v247, v147
	v_mul_f32_e32 v146, v47, v47
	v_mul_f32_e32 v147, v49, v49
	v_fma_f32 v44, v44, v247, v148
	v_fma_f32 v45, v45, v247, v149
	v_fmac_f32_e32 v146, v46, v46
	v_fmac_f32_e32 v147, v48, v48
	v_add_f32_e32 v146, v146, v147
	v_mul_f32_e32 v147, v43, v43
	v_mul_f32_e32 v148, v45, v45
	v_fmac_f32_e32 v147, v42, v42
	v_fmac_f32_e32 v148, v44, v44
	v_add_f32_e32 v147, v147, v148
	v_add_f32_e32 v154, v146, v147
	s_waitcnt lgkmcnt(0)
	v_lshlrev_b32_e32 v146, 16, v150
	v_and_b32_e32 v147, 0xffff0000, v150
	v_lshlrev_b32_e32 v148, 16, v151
	v_and_b32_e32 v149, 0xffff0000, v151
	v_fma_f32 v40, v40, v247, v148
	v_fma_f32 v41, v41, v247, v149
	v_fma_f32 v38, v38, v247, v146
	v_fma_f32 v39, v39, v247, v147
	v_lshlrev_b32_e32 v146, 16, v152
	v_and_b32_e32 v147, 0xffff0000, v152
	v_lshlrev_b32_e32 v148, 16, v153
	v_and_b32_e32 v149, 0xffff0000, v153
	v_fma_f32 v34, v34, v247, v146
	v_fma_f32 v35, v35, v247, v147
	v_mul_f32_e32 v146, v39, v39
	v_mul_f32_e32 v147, v41, v41
	v_fma_f32 v36, v36, v247, v148
	v_fma_f32 v37, v37, v247, v149
	v_fmac_f32_e32 v146, v38, v38
	v_fmac_f32_e32 v147, v40, v40
	v_add_f32_e32 v146, v146, v147
	v_mul_f32_e32 v147, v35, v35
	v_mul_f32_e32 v148, v37, v37
	v_fmac_f32_e32 v147, v34, v34
	v_fmac_f32_e32 v148, v36, v36
	v_add_f32_e32 v147, v147, v148
	v_add_f32_e32 v146, v146, v147
	v_add_f32_e32 v146, v154, v146
	ds_bpermute_b32 v147, v224, v146
	s_waitcnt lgkmcnt(0)
	v_add_f32_e32 v146, v146, v147
	ds_bpermute_b32 v147, v225, v146
	s_and_saveexec_b64 s[50:51], s[8:9]
	s_cbranch_execz .LBB0_741
	v_lshl_add_u64 v[148:149], v[206:207], 2, s[12:13]
	s_waitcnt lgkmcnt(0)
	v_add_f32_e32 v146, v146, v147
	global_atomic_add_f32 v[148:149], v146, off offset:576
; #define UNPK0(q_) ((f32x4){bf_lo((q_).x), bf_hi((q_).x), bf_lo((q_).y), bf_hi((q_).y)})
; #define UNPK1(q_) ((f32x4){bf_lo((q_).z), bf_hi((q_).z), bf_lo((q_).w), bf_hi((q_).w)})
;     __device__ __forceinline__ void operator()(f32x4 (&acc)[2][2][4][2], const Unit& u, int wr, int wc, int fr, int fq) const {
;     ...
;         for (int ai = 0; ai < 2; ++ai)
; #pragma unroll
;             for (int m = 0; m < 4; ++m) { const int row = row0 + ai * HALF + m * 16; float sq = 0.f;
;                 pi.stage(rx[ai][m][0], rx[ai][m][1]); const u32x4 x0 = pi.get(0), x1 = pi.get(1);
;                 asm volatile("" ::: "memory");
; #pragma unroll
;                 for (int bj = 0; bj < 2; ++bj) { const u32x4 z4 = bj ? x1 : x0;
;                     const f32x4 o0 = UNPK0(z4) + acc[ai][bj][m][0], o1 = UNPK1(z4) + acc[ai][bj][m][1];
;                     acc[ai][bj][m][0] = o0; acc[ai][bj][m][1] = o1;
;                     sq += ((o0[0] * o0[0] + o0[1] * o0[1]) + (o0[2] * o0[2] + o0[3] * o0[3])) + ((o1[0] * o1[0] + o1[1] * o1[1]) + (o1[2] * o1[2] + o1[3] * o1[3])); }
;                 sq += __shfl_xor(sq, 16); sq += __shfl_xor(sq, 32);
;                 if (fq == 0) atomicAdd(ss + row, sq); }
.LBB0_741:
	s_or_b64 exec, exec, s[50:51]
	ds_write_b128 v222, v[138:141]
	ds_write_b128 v222, v[142:145] offset:1152
	ds_read_b128 v[138:141], v223
	ds_read_b128 v[142:145], v223 offset:64
	s_waitcnt lgkmcnt(1)
	v_lshlrev_b32_e32 v146, 16, v138
	v_and_b32_e32 v147, 0xffff0000, v138
	v_lshlrev_b32_e32 v138, 16, v139
	v_and_b32_e32 v139, 0xffff0000, v139
	s_waitcnt vmcnt(4)
	v_fmamk_f32 v241, v241, 0x3a800000, v219
	v_rcp_f32_e32 v241, v241
	v_fmamk_f32 v242, v242, 0x3a800000, v219
	v_rcp_f32_e32 v242, v242
	v_fma_f32 v32, v32, v241, v138
	v_fma_f32 v33, v33, v241, v139
	v_fma_f32 v30, v30, v241, v146
	v_fma_f32 v31, v31, v241, v147
	v_lshlrev_b32_e32 v138, 16, v140
	v_and_b32_e32 v139, 0xffff0000, v140
	v_lshlrev_b32_e32 v140, 16, v141
	v_and_b32_e32 v141, 0xffff0000, v141
	v_fma_f32 v26, v26, v241, v138
	v_fma_f32 v27, v27, v241, v139
	v_mul_f32_e32 v138, v31, v31
	v_mul_f32_e32 v139, v33, v33
	v_fma_f32 v28, v28, v241, v140
	v_fma_f32 v29, v29, v241, v141
	v_fmac_f32_e32 v138, v30, v30
	v_fmac_f32_e32 v139, v32, v32
	v_add_f32_e32 v138, v138, v139
	v_mul_f32_e32 v139, v27, v27
	v_mul_f32_e32 v140, v29, v29
	v_fmac_f32_e32 v139, v26, v26
	v_fmac_f32_e32 v140, v28, v28
	v_add_f32_e32 v139, v139, v140
	v_add_f32_e32 v146, v138, v139
	s_waitcnt lgkmcnt(0)
	v_lshlrev_b32_e32 v138, 16, v142
	v_and_b32_e32 v139, 0xffff0000, v142
	v_lshlrev_b32_e32 v140, 16, v143
	v_and_b32_e32 v141, 0xffff0000, v143
	v_fma_f32 v24, v24, v241, v140
	v_fma_f32 v25, v25, v241, v141
	v_fma_f32 v22, v22, v241, v138
	v_fma_f32 v23, v23, v241, v139
	v_lshlrev_b32_e32 v138, 16, v144
	v_and_b32_e32 v139, 0xffff0000, v144
	v_lshlrev_b32_e32 v140, 16, v145
	v_and_b32_e32 v141, 0xffff0000, v145
	v_fma_f32 v18, v18, v241, v138
	v_fma_f32 v19, v19, v241, v139
	v_mul_f32_e32 v138, v23, v23
	v_mul_f32_e32 v139, v25, v25
	v_fma_f32 v20, v20, v241, v140
	v_fma_f32 v21, v21, v241, v141
	v_fmac_f32_e32 v138, v22, v22
	v_fmac_f32_e32 v139, v24, v24
	v_add_f32_e32 v138, v138, v139
	v_mul_f32_e32 v139, v19, v19
	v_mul_f32_e32 v140, v21, v21
	v_fmac_f32_e32 v139, v18, v18
	v_fmac_f32_e32 v140, v20, v20
	v_add_f32_e32 v139, v139, v140
	v_add_f32_e32 v138, v138, v139
	v_add_f32_e32 v138, v146, v138
	ds_bpermute_b32 v139, v224, v138
	s_waitcnt lgkmcnt(0)
	v_add_f32_e32 v138, v138, v139
	ds_bpermute_b32 v139, v225, v138
	s_and_saveexec_b64 s[50:51], s[8:9]
	s_cbranch_execz .LBB0_743
	v_lshl_add_u64 v[140:141], v[206:207], 2, s[12:13]
	s_waitcnt lgkmcnt(0)
	v_add_f32_e32 v138, v138, v139
	global_atomic_add_f32 v[140:141], v138, off offset:640
.LBB0_743:
	s_or_b64 exec, exec, s[50:51]
	ds_write_b128 v222, v[130:133]
	ds_write_b128 v222, v[134:137] offset:1152
	ds_read_b128 v[130:133], v223
	s_waitcnt lgkmcnt(3)
	ds_read_b128 v[138:141], v223 offset:64
	s_waitcnt lgkmcnt(1)
	v_lshlrev_b32_e32 v134, 16, v130
	v_and_b32_e32 v135, 0xffff0000, v130
	v_lshlrev_b32_e32 v130, 16, v131
	v_and_b32_e32 v131, 0xffff0000, v131
	v_fma_f32 v130, v16, v242, v130
	v_fma_f32 v131, v17, v242, v131
	v_fma_f32 v134, v14, v242, v134
	v_fma_f32 v135, v15, v242, v135
	v_lshlrev_b32_e32 v14, 16, v132
	v_and_b32_e32 v15, 0xffff0000, v132
	v_lshlrev_b32_e32 v16, 16, v133
	v_and_b32_e32 v17, 0xffff0000, v133
	v_fma_f32 v136, v10, v242, v14
	v_fma_f32 v137, v11, v242, v15
	v_mul_f32_e32 v10, v135, v135
	v_mul_f32_e32 v11, v131, v131
	v_fma_f32 v132, v12, v242, v16
	v_fma_f32 v133, v13, v242, v17
	v_fmac_f32_e32 v10, v134, v134
	v_fmac_f32_e32 v11, v130, v130
	v_add_f32_e32 v10, v10, v11
	v_mul_f32_e32 v11, v137, v137
	v_mul_f32_e32 v12, v133, v133
	v_fmac_f32_e32 v11, v136, v136
	v_fmac_f32_e32 v12, v132, v132
	v_add_f32_e32 v11, v11, v12
	v_add_f32_e32 v142, v10, v11
	s_waitcnt lgkmcnt(0)
	v_lshlrev_b32_e32 v12, 16, v138
	v_and_b32_e32 v13, 0xffff0000, v138
	v_lshlrev_b32_e32 v10, 16, v139
	v_and_b32_e32 v11, 0xffff0000, v139
	v_fma_f32 v10, v8, v242, v10
	v_fma_f32 v11, v9, v242, v11
	v_fma_f32 v14, v6, v242, v12
	v_fma_f32 v15, v7, v242, v13
	v_lshlrev_b32_e32 v6, 16, v140
	v_and_b32_e32 v7, 0xffff0000, v140
	v_lshlrev_b32_e32 v8, 16, v141
	v_and_b32_e32 v9, 0xffff0000, v141
	v_fma_f32 v16, v2, v242, v6
	v_fma_f32 v17, v3, v242, v7
	v_mul_f32_e32 v2, v15, v15
	v_mul_f32_e32 v3, v11, v11
	v_fma_f32 v12, v4, v242, v8
	v_fma_f32 v13, v5, v242, v9
	v_fmac_f32_e32 v2, v14, v14
	v_fmac_f32_e32 v3, v10, v10
	v_add_f32_e32 v2, v2, v3
	v_mul_f32_e32 v3, v17, v17
	v_mul_f32_e32 v4, v13, v13
	v_fmac_f32_e32 v3, v16, v16
	v_fmac_f32_e32 v4, v12, v12
	v_add_f32_e32 v3, v3, v4
	v_add_f32_e32 v2, v2, v3
	v_add_f32_e32 v2, v142, v2
	ds_bpermute_b32 v3, v224, v2
	s_waitcnt lgkmcnt(0)
	v_add_f32_e32 v2, v2, v3
	ds_bpermute_b32 v3, v225, v2
	s_and_saveexec_b64 s[50:51], s[8:9]
	s_cbranch_execz .LBB0_745
	v_lshl_add_u64 v[4:5], v[206:207], 2, s[12:13]
	s_waitcnt lgkmcnt(0)
	v_add_f32_e32 v2, v2, v3
	global_atomic_add_f32 v[4:5], v2, off offset:704
